# baseline (speedup 1.0000x reference)
; template <int MODE>
; __device__ __forceinline__ void attn_unit(const UnitP& P, ALAS char* lds, const float* __restrict__ sub_gain, const int wv0, unsigned& hgen, unsigned* qctr, const int xcd) {
;     ...
;         if (active && map == 0) {
;             const float inv = 1.f / lsum;
;             float ss = 0.f;
; #pragma unroll
;             for (int d0 = 0; d0 < 4; ++d0)
; #pragma unroll
;                 for (int r = 0; r < 16; ++r) { const float v = o[d0][r] * inv - ex[(d0 * 16 + r) * 64]; o[d0][r] = v; ss += v * v; }
.LBB0_330:
	s_cmp_eq_u32 s12, 0
	s_cselect_b64 s[6:7], -1, 0
	s_and_b64 s[4:5], s[4:5], s[6:7]
	s_andn2_b64 vcc, exec, s[4:5]
	s_cbranch_vccnz .LBB0_334
	v_div_scale_f32 v65, s[4:5], v64, v64, 1.0
	v_rcp_f32_e32 v66, v65
	v_div_scale_f32 v67, vcc, 1.0, v64, 1.0
	v_readlane_b32 s2, v252, 44
	v_fma_f32 v68, -v65, v66, 1.0
	v_fmac_f32_e32 v66, v68, v66
	v_mul_f32_e32 v68, v67, v66
	v_fma_f32 v69, -v65, v68, v67
	v_fmac_f32_e32 v68, v69, v66
	v_fma_f32 v65, -v65, v68, v67
	v_div_fmas_f32 v65, v65, v66, v68
	ds_read2st64_b32 v[66:67], v79 offset1:1
	v_div_fixup_f32 v78, v65, v64, 1.0
	ds_read2st64_b32 v[64:65], v79 offset0:2 offset1:3
	ds_read2st64_b32 v[68:69], v79 offset0:4 offset1:5
	ds_read2st64_b32 v[70:71], v79 offset0:6 offset1:7
	v_cmp_gt_u32_e32 vcc, s2, v174
	s_waitcnt lgkmcnt(0)
	v_pk_fma_f32 v[74:75], v[48:49], v[78:79], v[66:67] op_sel_hi:[1,0,1] neg_lo:[0,0,1] neg_hi:[0,0,1]
	s_nop 0
	v_mul_f32_e32 v48, v75, v75
	v_pk_fma_f32 v[48:49], v[74:75], v[74:75], v[48:49] op_sel_hi:[1,1,0]
	v_pk_fma_f32 v[76:77], v[50:51], v[78:79], v[64:65] op_sel_hi:[1,0,1] neg_lo:[0,0,1] neg_hi:[0,0,1]
	v_pk_fma_f32 v[72:73], v[52:53], v[78:79], v[68:69] op_sel_hi:[1,0,1] neg_lo:[0,0,1] neg_hi:[0,0,1]
	v_pk_fma_f32 v[48:49], v[76:77], v[76:77], v[48:49]
	v_mul_f32_e32 v50, v77, v77
	v_pk_add_f32 v[48:49], v[48:49], v[50:51] op_sel_hi:[1,0]
	ds_read2st64_b32 v[52:53], v79 offset0:8 offset1:9
	v_pk_fma_f32 v[48:49], v[72:73], v[72:73], v[48:49]
	v_mul_f32_e32 v50, v73, v73
	v_pk_add_f32 v[48:49], v[48:49], v[50:51] op_sel_hi:[1,0]
	v_pk_fma_f32 v[70:71], v[54:55], v[78:79], v[70:71] op_sel_hi:[1,0,1] neg_lo:[0,0,1] neg_hi:[0,0,1]
	s_waitcnt lgkmcnt(0)
	v_pk_fma_f32 v[66:67], v[56:57], v[78:79], v[52:53] op_sel_hi:[1,0,1] neg_lo:[0,0,1] neg_hi:[0,0,1]
	v_pk_fma_f32 v[48:49], v[70:71], v[70:71], v[48:49]
	v_mul_f32_e32 v50, v71, v71
	v_pk_add_f32 v[48:49], v[48:49], v[50:51] op_sel_hi:[1,0]
	ds_read2st64_b32 v[50:51], v79 offset0:10 offset1:11
	ds_read2st64_b32 v[54:55], v79 offset0:12 offset1:13
	ds_read2st64_b32 v[80:81], v79 offset0:14 offset1:15
	v_pk_fma_f32 v[48:49], v[66:67], v[66:67], v[48:49]
	v_mul_f32_e32 v52, v67, v67
	v_pk_add_f32 v[48:49], v[48:49], v[52:53] op_sel_hi:[1,0]
	s_waitcnt lgkmcnt(0)
	v_pk_fma_f32 v[68:69], v[58:59], v[78:79], v[50:51] op_sel_hi:[1,0,1] neg_lo:[0,0,1] neg_hi:[0,0,1]
	v_pk_fma_f32 v[64:65], v[60:61], v[78:79], v[54:55] op_sel_hi:[1,0,1] neg_lo:[0,0,1] neg_hi:[0,0,1]
	v_pk_fma_f32 v[48:49], v[68:69], v[68:69], v[48:49]
	v_mul_f32_e32 v50, v69, v69
	v_pk_add_f32 v[48:49], v[48:49], v[50:51] op_sel_hi:[1,0]
	ds_read2st64_b32 v[52:53], v79 offset0:16 offset1:17
	v_pk_fma_f32 v[48:49], v[64:65], v[64:65], v[48:49]
	v_mul_f32_e32 v50, v65, v65
	v_pk_add_f32 v[48:49], v[48:49], v[50:51] op_sel_hi:[1,0]
	v_pk_fma_f32 v[62:63], v[62:63], v[78:79], v[80:81] op_sel_hi:[1,0,1] neg_lo:[0,0,1] neg_hi:[0,0,1]
	s_waitcnt lgkmcnt(0)
	v_pk_fma_f32 v[58:59], v[32:33], v[78:79], v[52:53] op_sel_hi:[1,0,1] neg_lo:[0,0,1] neg_hi:[0,0,1]
	v_pk_fma_f32 v[48:49], v[62:63], v[62:63], v[48:49]
	v_mul_f32_e32 v50, v63, v63
	v_pk_add_f32 v[48:49], v[48:49], v[50:51] op_sel_hi:[1,0]
	ds_read2st64_b32 v[50:51], v79 offset0:18 offset1:19
	ds_read2st64_b32 v[54:55], v79 offset0:20 offset1:21
	ds_read2st64_b32 v[80:81], v79 offset0:22 offset1:23
	v_pk_fma_f32 v[32:33], v[58:59], v[58:59], v[48:49]
	v_mul_f32_e32 v48, v59, v59
	v_pk_add_f32 v[32:33], v[32:33], v[48:49] op_sel_hi:[1,0]
	s_waitcnt lgkmcnt(0)
	v_pk_fma_f32 v[60:61], v[34:35], v[78:79], v[50:51] op_sel_hi:[1,0,1] neg_lo:[0,0,1] neg_hi:[0,0,1]
	v_pk_fma_f32 v[56:57], v[36:37], v[78:79], v[54:55] op_sel_hi:[1,0,1] neg_lo:[0,0,1] neg_hi:[0,0,1]
	v_pk_fma_f32 v[32:33], v[60:61], v[60:61], v[32:33]
	v_mul_f32_e32 v34, v61, v61
	v_pk_add_f32 v[32:33], v[32:33], v[34:35] op_sel_hi:[1,0]
	ds_read2st64_b32 v[36:37], v79 offset0:24 offset1:25
	v_pk_fma_f32 v[32:33], v[56:57], v[56:57], v[32:33]
	v_mul_f32_e32 v34, v57, v57
	v_pk_add_f32 v[32:33], v[32:33], v[34:35] op_sel_hi:[1,0]
	v_pk_fma_f32 v[54:55], v[38:39], v[78:79], v[80:81] op_sel_hi:[1,0,1] neg_lo:[0,0,1] neg_hi:[0,0,1]
	s_waitcnt lgkmcnt(0)
	v_pk_fma_f32 v[50:51], v[40:41], v[78:79], v[36:37] op_sel_hi:[1,0,1] neg_lo:[0,0,1] neg_hi:[0,0,1]
	v_pk_fma_f32 v[32:33], v[54:55], v[54:55], v[32:33]
	v_mul_f32_e32 v34, v55, v55
	v_pk_add_f32 v[32:33], v[32:33], v[34:35] op_sel_hi:[1,0]
	ds_read2st64_b32 v[34:35], v79 offset0:26 offset1:27
	ds_read2st64_b32 v[38:39], v79 offset0:28 offset1:29
	ds_read2st64_b32 v[80:81], v79 offset0:30 offset1:31
	v_pk_fma_f32 v[32:33], v[50:51], v[50:51], v[32:33]
	v_mul_f32_e32 v36, v51, v51
	v_pk_add_f32 v[32:33], v[32:33], v[36:37] op_sel_hi:[1,0]
	s_waitcnt lgkmcnt(0)
	v_pk_fma_f32 v[52:53], v[42:43], v[78:79], v[34:35] op_sel_hi:[1,0,1] neg_lo:[0,0,1] neg_hi:[0,0,1]
	v_pk_fma_f32 v[48:49], v[44:45], v[78:79], v[38:39] op_sel_hi:[1,0,1] neg_lo:[0,0,1] neg_hi:[0,0,1]
	v_pk_fma_f32 v[32:33], v[52:53], v[52:53], v[32:33]
	v_mul_f32_e32 v34, v53, v53
	v_pk_add_f32 v[32:33], v[32:33], v[34:35] op_sel_hi:[1,0]
	ds_read2st64_b32 v[36:37], v79 offset0:32 offset1:33
	v_pk_fma_f32 v[32:33], v[48:49], v[48:49], v[32:33]
	v_mul_f32_e32 v34, v49, v49
	v_pk_add_f32 v[32:33], v[32:33], v[34:35] op_sel_hi:[1,0]
	v_pk_fma_f32 v[44:45], v[46:47], v[78:79], v[80:81] op_sel_hi:[1,0,1] neg_lo:[0,0,1] neg_hi:[0,0,1]
	s_waitcnt lgkmcnt(0)
	v_pk_fma_f32 v[40:41], v[16:17], v[78:79], v[36:37] op_sel_hi:[1,0,1] neg_lo:[0,0,1] neg_hi:[0,0,1]
	v_pk_fma_f32 v[32:33], v[44:45], v[44:45], v[32:33]
	v_mul_f32_e32 v34, v45, v45
	v_pk_add_f32 v[32:33], v[32:33], v[34:35] op_sel_hi:[1,0]
	ds_read2st64_b32 v[34:35], v79 offset0:34 offset1:35
	ds_read2st64_b32 v[38:39], v79 offset0:36 offset1:37
	ds_read2st64_b32 v[46:47], v79 offset0:38 offset1:39
	v_pk_fma_f32 v[16:17], v[40:41], v[40:41], v[32:33]
	v_mul_f32_e32 v32, v41, v41
	v_pk_add_f32 v[16:17], v[16:17], v[32:33] op_sel_hi:[1,0]
	s_waitcnt lgkmcnt(0)
; __device__ __forceinline__ float sum32(float v) { auto rr = __builtin_amdgcn_permlane32_swap(__float_as_uint(v), __float_as_uint(v), false, false); return __uint_as_float(rr[0]) + __uint_as_float(rr[1]); }
; template <int MODE>
; __device__ __forceinline__ void attn_unit(const UnitP& P, ALAS char* lds, const float* __restrict__ sub_gain, const int wv0, unsigned& hgen, unsigned* qctr, const int xcd) {
;     ...
;                 for (int r = 0; r < 16; ++r) { const float v = o[d0][r] * inv - ex[(d0 * 16 + r) * 64]; o[d0][r] = v; ss += v * v; }
;             ss = sum32(ss);
;             const float rn = rsqrtf(ss * (1.f / 128.f) + 1e-6f) * 0.8f;
;             if (qrow < P.nq && P.dry == 0) {
	v_pk_fma_f32 v[42:43], v[18:19], v[78:79], v[34:35] op_sel_hi:[1,0,1] neg_lo:[0,0,1] neg_hi:[0,0,1]
	v_pk_fma_f32 v[38:39], v[20:21], v[78:79], v[38:39] op_sel_hi:[1,0,1] neg_lo:[0,0,1] neg_hi:[0,0,1]
	v_pk_fma_f32 v[16:17], v[42:43], v[42:43], v[16:17]
	v_mul_f32_e32 v18, v43, v43
	v_pk_add_f32 v[16:17], v[16:17], v[18:19] op_sel_hi:[1,0]
	ds_read2st64_b32 v[20:21], v79 offset0:40 offset1:41
	v_pk_fma_f32 v[16:17], v[38:39], v[38:39], v[16:17]
	v_mul_f32_e32 v18, v39, v39
	v_pk_add_f32 v[16:17], v[16:17], v[18:19] op_sel_hi:[1,0]
	v_pk_fma_f32 v[36:37], v[22:23], v[78:79], v[46:47] op_sel_hi:[1,0,1] neg_lo:[0,0,1] neg_hi:[0,0,1]
	s_waitcnt lgkmcnt(0)
	v_pk_fma_f32 v[32:33], v[24:25], v[78:79], v[20:21] op_sel_hi:[1,0,1] neg_lo:[0,0,1] neg_hi:[0,0,1]
	v_pk_fma_f32 v[16:17], v[36:37], v[36:37], v[16:17]
	v_mul_f32_e32 v18, v37, v37
	v_pk_add_f32 v[16:17], v[16:17], v[18:19] op_sel_hi:[1,0]
	ds_read2st64_b32 v[18:19], v79 offset0:42 offset1:43
	ds_read2st64_b32 v[22:23], v79 offset0:44 offset1:45
	ds_read2st64_b32 v[46:47], v79 offset0:46 offset1:47
	v_pk_fma_f32 v[16:17], v[32:33], v[32:33], v[16:17]
	v_mul_f32_e32 v20, v33, v33
	v_pk_add_f32 v[16:17], v[16:17], v[20:21] op_sel_hi:[1,0]
	s_waitcnt lgkmcnt(0)
	v_pk_fma_f32 v[34:35], v[26:27], v[78:79], v[18:19] op_sel_hi:[1,0,1] neg_lo:[0,0,1] neg_hi:[0,0,1]
	v_pk_fma_f32 v[26:27], v[28:29], v[78:79], v[22:23] op_sel_hi:[1,0,1] neg_lo:[0,0,1] neg_hi:[0,0,1]
	v_pk_fma_f32 v[16:17], v[34:35], v[34:35], v[16:17]
	v_mul_f32_e32 v18, v35, v35
	v_pk_add_f32 v[16:17], v[16:17], v[18:19] op_sel_hi:[1,0]
	ds_read2st64_b32 v[20:21], v79 offset0:48 offset1:49
	v_pk_fma_f32 v[16:17], v[26:27], v[26:27], v[16:17]
	v_mul_f32_e32 v18, v27, v27
	v_pk_add_f32 v[16:17], v[16:17], v[18:19] op_sel_hi:[1,0]
	v_pk_fma_f32 v[24:25], v[30:31], v[78:79], v[46:47] op_sel_hi:[1,0,1] neg_lo:[0,0,1] neg_hi:[0,0,1]
	s_waitcnt lgkmcnt(0)
	v_pk_fma_f32 v[20:21], v[0:1], v[78:79], v[20:21] op_sel_hi:[1,0,1] neg_lo:[0,0,1] neg_hi:[0,0,1]
	v_pk_fma_f32 v[16:17], v[24:25], v[24:25], v[16:17]
	v_mul_f32_e32 v18, v25, v25
	v_pk_add_f32 v[16:17], v[16:17], v[18:19] op_sel_hi:[1,0]
	ds_read2st64_b32 v[18:19], v79 offset0:50 offset1:51
	ds_read2st64_b32 v[28:29], v79 offset0:52 offset1:53
	ds_read2st64_b32 v[30:31], v79 offset0:54 offset1:55
	v_pk_fma_f32 v[0:1], v[20:21], v[20:21], v[16:17]
	v_mul_f32_e32 v16, v21, v21
	v_pk_add_f32 v[0:1], v[0:1], v[16:17] op_sel_hi:[1,0]
	s_waitcnt lgkmcnt(0)
	v_pk_fma_f32 v[22:23], v[2:3], v[78:79], v[18:19] op_sel_hi:[1,0,1] neg_lo:[0,0,1] neg_hi:[0,0,1]
	v_pk_fma_f32 v[18:19], v[4:5], v[78:79], v[28:29] op_sel_hi:[1,0,1] neg_lo:[0,0,1] neg_hi:[0,0,1]
	v_pk_fma_f32 v[0:1], v[22:23], v[22:23], v[0:1]
	v_mul_f32_e32 v2, v23, v23
	v_pk_add_f32 v[0:1], v[0:1], v[2:3] op_sel_hi:[1,0]
	ds_read2st64_b32 v[4:5], v79 offset0:56 offset1:57
	v_pk_fma_f32 v[0:1], v[18:19], v[18:19], v[0:1]
	v_mul_f32_e32 v2, v19, v19
	v_pk_add_f32 v[0:1], v[0:1], v[2:3] op_sel_hi:[1,0]
	v_pk_fma_f32 v[16:17], v[6:7], v[78:79], v[30:31] op_sel_hi:[1,0,1] neg_lo:[0,0,1] neg_hi:[0,0,1]
	s_waitcnt lgkmcnt(0)
	v_pk_fma_f32 v[8:9], v[8:9], v[78:79], v[4:5] op_sel_hi:[1,0,1] neg_lo:[0,0,1] neg_hi:[0,0,1]
	v_pk_fma_f32 v[0:1], v[16:17], v[16:17], v[0:1]
	v_mul_f32_e32 v2, v17, v17
	v_pk_add_f32 v[0:1], v[0:1], v[2:3] op_sel_hi:[1,0]
	ds_read2st64_b32 v[2:3], v79 offset0:58 offset1:59
	ds_read2st64_b32 v[6:7], v79 offset0:60 offset1:61
	ds_read2st64_b32 v[28:29], v79 offset0:62 offset1:63
	v_pk_fma_f32 v[0:1], v[8:9], v[8:9], v[0:1]
	v_mul_f32_e32 v4, v9, v9
	v_pk_add_f32 v[0:1], v[0:1], v[4:5] op_sel_hi:[1,0]
	s_waitcnt lgkmcnt(0)
	v_pk_fma_f32 v[10:11], v[10:11], v[78:79], v[2:3] op_sel_hi:[1,0,1] neg_lo:[0,0,1] neg_hi:[0,0,1]
	s_nop 0
	v_pk_fma_f32 v[0:1], v[10:11], v[10:11], v[0:1]
	v_mul_f32_e32 v2, v11, v11
	v_pk_add_f32 v[0:1], v[0:1], v[2:3] op_sel_hi:[1,0]
	v_pk_fma_f32 v[2:3], v[12:13], v[78:79], v[6:7] op_sel_hi:[1,0,1] neg_lo:[0,0,1] neg_hi:[0,0,1]
	s_nop 0
	v_pk_fma_f32 v[0:1], v[2:3], v[2:3], v[0:1]
	v_mul_f32_e32 v4, v3, v3
	v_pk_add_f32 v[4:5], v[0:1], v[4:5] op_sel_hi:[1,0]
	v_pk_fma_f32 v[0:1], v[14:15], v[78:79], v[28:29] op_sel_hi:[1,0,1] neg_lo:[0,0,1] neg_hi:[0,0,1]
	s_nop 0
	v_pk_fma_f32 v[4:5], v[0:1], v[0:1], v[4:5]
	v_mul_f32_e32 v6, v1, v1
	v_pk_add_f32 v[4:5], v[4:5], v[6:7] op_sel_hi:[1,0]
	s_nop 0
	v_mov_b32_e32 v5, v4
	s_nop 1
	v_permlane32_swap_b32_e32 v4, v5
	s_and_saveexec_b64 s[10:11], vcc
	s_cbranch_execz .LBB0_333
; __device__ __forceinline__ float sum32(float v) { auto rr = __builtin_amdgcn_permlane32_swap(__float_as_uint(v), __float_as_uint(v), false, false); return __uint_as_float(rr[0]) + __uint_as_float(rr[1]); }
; __device__ __forceinline__ unsigned cvtpk(float lo, float hi) { f32x2 v = {lo, hi}; bf16x2_t b = __builtin_convertvector(v, bf16x2_t); return __builtin_bit_cast(unsigned, b); }
; __device__ __forceinline__ float bf2f(unsigned u16) { return __uint_as_float(u16 << 16); }
; __device__ __forceinline__ float silu(float g) { return g / (1.f + __expf(-g)); }
; template <int MODE>
; __device__ __forceinline__ void attn_unit(const UnitP& P, ALAS char* lds, const float* __restrict__ sub_gain, const int wv0, unsigned& hgen, unsigned* qctr, const int xcd) {
;     ...
;             ss = sum32(ss);
;             const float rn = rsqrtf(ss * (1.f / 128.f) + 1e-6f) * 0.8f;
;             if (qrow < P.nq && P.dry == 0) {
;                 const bf16_t* gp = P.G + (size_t)qrow * 8192 + 4 * hi;
;                 bf16_t* mp = P.Mo + (size_t)qrow * 2048 + 4 * hi;
; #pragma unroll
;                 for (int d0 = 0; d0 < 4; ++d0)
; #pragma unroll
;                     for (int g = 0; g < 4; ++g) {
;                         const u32x2 gg = *(const u32x2*)(gp + 32 * d0 + 8 * g);
;                         const f32x4 sg = *(const f32x4*)(sub_gain + 32 * d0 + 8 * g + 4 * hi);
;                         const float y0 = o[d0][4 * g + 0] * rn * sg[0] * silu(bf2f(gg.x & 0xffffu)), y1 = o[d0][4 * g + 1] * rn * sg[1] * silu(bf2f(gg.x >> 16));
;                         const float y2 = o[d0][4 * g + 2] * rn * sg[2] * silu(bf2f(gg.y & 0xffffu)), y3 = o[d0][4 * g + 3] * rn * sg[3] * silu(bf2f(gg.y >> 16));
;                         u32x2 w; w.x = cvtpk(y0, y1); w.y = cvtpk(y2, y3);
;                         *(u32x2*)(mp + 32 * d0 + 8 * g) = w;
	v_readlane_b32 s4, v252, 40
	v_mov_b32_e32 v163, v177
	v_readlane_b32 s5, v252, 41
	v_lshlrev_b32_e32 v176, 1, v178
	v_lshlrev_b32_e32 v13, 2, v178
	v_lshl_add_u64 v[6:7], s[4:5], 0, v[162:163]
	v_lshl_add_u64 v[6:7], v[6:7], 0, v[176:177]
	global_load_dwordx2 v[14:15], v[6:7], off
	global_load_dwordx2 v[102:103], v[6:7], off offset:16
	global_load_dwordx2 v[104:105], v[6:7], off offset:32
	global_load_dwordx2 v[106:107], v[6:7], off offset:48
	global_load_dwordx2 v[108:109], v[6:7], off offset:64
	global_load_dwordx2 v[110:111], v[6:7], off offset:80
	global_load_dwordx2 v[112:113], v[6:7], off offset:96
	global_load_dwordx2 v[114:115], v[6:7], off offset:112
	global_load_dwordx2 v[116:117], v[6:7], off offset:128
	global_load_dwordx2 v[118:119], v[6:7], off offset:144
	global_load_dwordx2 v[120:121], v[6:7], off offset:160
	global_load_dwordx2 v[122:123], v[6:7], off offset:176
	global_load_dwordx2 v[124:125], v[6:7], off offset:192
	global_load_dwordx2 v[126:127], v[6:7], off offset:208
	global_load_dwordx2 v[128:129], v[6:7], off offset:224
	global_load_dwordx2 v[130:131], v[6:7], off offset:240
	v_readlane_b32 s4, v252, 1
	v_readlane_b32 s5, v252, 2
	s_load_dwordx8 s[12:19], s[4:5], 0x70
	v_add_f32_e32 v12, v4, v5
	s_mov_b32 s2, 0x800000
	v_fmamk_f32 v12, v12, 0x3c000000, v196
	v_mul_f32_e32 v46, 0x4b800000, v12
	s_waitcnt lgkmcnt(0)
	global_load_dwordx4 v[28:31], v13, s[12:13]
	global_load_dwordx4 v[78:81], v13, s[12:13] offset:32
	v_cmp_gt_f32_e32 vcc, s2, v12
	v_readlane_b32 s4, v252, 42
	v_lshlrev_b32_e32 v4, 12, v174
	v_cndmask_b32_e32 v12, v12, v46, vcc
	v_rsq_f32_e32 v12, v12
	v_mov_b32_e32 v5, v177
	v_readlane_b32 s5, v252, 43
	v_mul_f32_e32 v46, 0x45800000, v12
	v_cndmask_b32_e32 v12, v12, v46, vcc
	v_mul_f32_e32 v12, 0x3f4ccccd, v12
	v_pk_mul_f32 v[46:47], v[74:75], v[12:13] op_sel_hi:[1,0]
	v_pk_mul_f32 v[74:75], v[76:77], v[12:13] op_sel_hi:[1,0]
	v_lshl_add_u64 v[4:5], s[4:5], 0, v[4:5]
	v_lshl_add_u64 v[4:5], v[4:5], 0, v[176:177]
	v_pk_mul_f32 v[42:43], v[42:43], v[12:13] op_sel_hi:[1,0]
	v_pk_mul_f32 v[40:41], v[40:41], v[12:13] op_sel_hi:[1,0]
	v_pk_mul_f32 v[34:35], v[34:35], v[12:13] op_sel_hi:[1,0]
	v_pk_mul_f32 v[32:33], v[32:33], v[12:13] op_sel_hi:[1,0]
	v_pk_mul_f32 v[26:27], v[26:27], v[12:13] op_sel_hi:[1,0]
	v_pk_mul_f32 v[24:25], v[24:25], v[12:13] op_sel_hi:[1,0]
	v_pk_mul_f32 v[22:23], v[22:23], v[12:13] op_sel_hi:[1,0]
	v_pk_mul_f32 v[20:21], v[20:21], v[12:13] op_sel_hi:[1,0]
	v_pk_mul_f32 v[18:19], v[18:19], v[12:13] op_sel_hi:[1,0]
	v_pk_mul_f32 v[16:17], v[16:17], v[12:13] op_sel_hi:[1,0]
	v_pk_mul_f32 v[8:9], v[8:9], v[12:13] op_sel_hi:[1,0]
	v_pk_mul_f32 v[10:11], v[10:11], v[12:13] op_sel_hi:[1,0]
	s_waitcnt vmcnt(0)
	v_lshlrev_b32_e32 v82, 16, v14
	v_and_b32_e32 v83, 0xffff0000, v14
	v_lshlrev_b32_e32 v84, 16, v15
	v_and_b32_e32 v85, 0xffff0000, v15
	v_mul_f32_e32 v14, 0xbfb8aa3b, v82
	v_mul_f32_e32 v15, 0xbfb8aa3b, v83
	v_exp_f32_e32 v14, v14
	v_exp_f32_e32 v15, v15
	v_mul_f32_e32 v76, 0xbfb8aa3b, v84
	v_mul_f32_e32 v77, 0xbfb8aa3b, v85
	v_exp_f32_e32 v76, v76
	v_exp_f32_e32 v77, v77
	v_pk_add_f32 v[14:15], v[14:15], 1.0 op_sel_hi:[1,0]
	v_pk_mul_f32 v[30:31], v[74:75], v[30:31]
	v_div_scale_f32 v74, s[4:5], v15, v15, v83
	v_pk_mul_f32 v[28:29], v[46:47], v[28:29]
	v_pk_add_f32 v[46:47], v[76:77], 1.0 op_sel_hi:[1,0]
	v_div_scale_f32 v76, s[4:5], v14, v14, v82
	v_rcp_f32_e32 v90, v74
	v_div_scale_f32 v86, s[6:7], v47, v47, v85
	v_rcp_f32_e32 v91, v76
	v_div_scale_f32 v88, s[8:9], v46, v46, v84
	v_rcp_f32_e32 v92, v86
	v_rcp_f32_e32 v93, v88
	v_fma_f32 v94, -v74, v90, 1.0
	v_div_scale_f32 v75, vcc, v83, v15, v83
	v_fma_f32 v95, -v76, v91, 1.0
	v_fmac_f32_e32 v90, v94, v90
	v_div_scale_f32 v77, s[4:5], v82, v14, v82
	v_fma_f32 v96, -v86, v92, 1.0
	v_fmac_f32_e32 v91, v95, v91
	v_mul_f32_e32 v94, v75, v90
	v_div_scale_f32 v87, s[6:7], v85, v47, v85
	v_fma_f32 v97, -v88, v93, 1.0
	v_fmac_f32_e32 v92, v96, v92
	v_mul_f32_e32 v95, v77, v91
	v_fma_f32 v98, -v74, v94, v75
	v_div_scale_f32 v89, s[8:9], v84, v46, v84
	v_fmac_f32_e32 v93, v97, v93
	v_mul_f32_e32 v96, v87, v92
	v_fma_f32 v99, -v76, v95, v77
	v_fmac_f32_e32 v94, v98, v90
	v_mul_f32_e32 v97, v89, v93
	v_fma_f32 v100, -v86, v96, v87
	v_fmac_f32_e32 v95, v99, v91
	v_fma_f32 v74, -v74, v94, v75
	v_fma_f32 v101, -v88, v97, v89
	v_fmac_f32_e32 v96, v100, v92
	v_fma_f32 v75, -v76, v95, v77
	v_div_fmas_f32 v74, v74, v90, v94
	s_mov_b64 vcc, s[4:5]
	v_fmac_f32_e32 v97, v101, v93
	v_fma_f32 v76, -v86, v96, v87
	v_div_fixup_f32 v15, v74, v15, v83
	v_div_fmas_f32 v74, v75, v91, v95
	s_mov_b64 vcc, s[6:7]
	v_fma_f32 v77, -v88, v97, v89
	v_div_fixup_f32 v14, v74, v14, v82
	v_div_fmas_f32 v74, v76, v92, v96
	s_mov_b64 vcc, s[8:9]
	v_pk_mul_f32 v[14:15], v[28:29], v[14:15]
	v_div_fmas_f32 v28, v77, v93, v97
	v_div_fixup_f32 v29, v74, v47, v85
	v_div_fixup_f32 v28, v28, v46, v84
	v_pk_mul_f32 v[28:29], v[30:31], v[28:29]
	v_cvt_pk_bf16_f32 v14, v14, v15
	v_cvt_pk_bf16_f32 v15, v28, v29
	v_mov_b32_e32 v132, v14
	v_mov_b32_e32 v133, v15
	v_mov_b32_e32 v14, v102
	v_mov_b32_e32 v15, v103
	v_pk_mul_f32 v[30:31], v[70:71], v[12:13] op_sel_hi:[1,0]
	v_pk_mul_f32 v[28:29], v[72:73], v[12:13] op_sel_hi:[1,0]
	v_pk_mul_f32 v[30:31], v[30:31], v[80:81]
	v_pk_mul_f32 v[28:29], v[28:29], v[78:79]
	v_lshlrev_b32_e32 v70, 16, v14
	v_and_b32_e32 v71, 0xffff0000, v14
	v_lshlrev_b32_e32 v72, 16, v15
	v_and_b32_e32 v73, 0xffff0000, v15
	v_mul_f32_e32 v14, 0xbfb8aa3b, v70
	v_mul_f32_e32 v15, 0xbfb8aa3b, v71
	v_exp_f32_e32 v14, v14
	v_exp_f32_e32 v15, v15
	v_mul_f32_e32 v46, 0xbfb8aa3b, v72
	v_mul_f32_e32 v47, 0xbfb8aa3b, v73
	v_exp_f32_e32 v46, v46
	v_exp_f32_e32 v47, v47
; __device__ __forceinline__ unsigned cvtpk(float lo, float hi) { f32x2 v = {lo, hi}; bf16x2_t b = __builtin_convertvector(v, bf16x2_t); return __builtin_bit_cast(unsigned, b); }
; __device__ __forceinline__ float bf2f(unsigned u16) { return __uint_as_float(u16 << 16); }
; __device__ __forceinline__ float silu(float g) { return g / (1.f + __expf(-g)); }
; template <int MODE>
; __device__ __forceinline__ void attn_unit(const UnitP& P, ALAS char* lds, const float* __restrict__ sub_gain, const int wv0, unsigned& hgen, unsigned* qctr, const int xcd) {
;     ...
;                 for (int d0 = 0; d0 < 4; ++d0)
; #pragma unroll
;                     for (int g = 0; g < 4; ++g) {
;                         const u32x2 gg = *(const u32x2*)(gp + 32 * d0 + 8 * g);
;                         const f32x4 sg = *(const f32x4*)(sub_gain + 32 * d0 + 8 * g + 4 * hi);
;                         const float y0 = o[d0][4 * g + 0] * rn * sg[0] * silu(bf2f(gg.x & 0xffffu)), y1 = o[d0][4 * g + 1] * rn * sg[1] * silu(bf2f(gg.x >> 16));
;                         const float y2 = o[d0][4 * g + 2] * rn * sg[2] * silu(bf2f(gg.y & 0xffffu)), y3 = o[d0][4 * g + 3] * rn * sg[3] * silu(bf2f(gg.y >> 16));
;                         u32x2 w; w.x = cvtpk(y0, y1); w.y = cvtpk(y2, y3);
;                         *(u32x2*)(mp + 32 * d0 + 8 * g) = w;
	v_pk_add_f32 v[14:15], v[14:15], 1.0 op_sel_hi:[1,0]
	v_pk_add_f32 v[46:47], v[46:47], 1.0 op_sel_hi:[1,0]
	v_div_scale_f32 v74, s[4:5], v15, v15, v71
	v_div_scale_f32 v76, s[4:5], v14, v14, v70
	v_rcp_f32_e32 v82, v74
	v_div_scale_f32 v78, s[6:7], v47, v47, v73
	v_rcp_f32_e32 v83, v76
	v_div_scale_f32 v80, s[8:9], v46, v46, v72
	v_rcp_f32_e32 v84, v78
	v_rcp_f32_e32 v85, v80
	v_fma_f32 v86, -v74, v82, 1.0
	v_div_scale_f32 v75, vcc, v71, v15, v71
	v_fma_f32 v87, -v76, v83, 1.0
	v_fmac_f32_e32 v82, v86, v82
	v_div_scale_f32 v77, s[4:5], v70, v14, v70
	v_fma_f32 v88, -v78, v84, 1.0
	v_fmac_f32_e32 v83, v87, v83
	v_mul_f32_e32 v86, v75, v82
	v_div_scale_f32 v79, s[6:7], v73, v47, v73
	v_fma_f32 v89, -v80, v85, 1.0
	v_fmac_f32_e32 v84, v88, v84
	v_mul_f32_e32 v87, v77, v83
	v_fma_f32 v90, -v74, v86, v75
	v_div_scale_f32 v81, s[8:9], v72, v46, v72
	v_fmac_f32_e32 v85, v89, v85
	v_mul_f32_e32 v88, v79, v84
	v_fma_f32 v91, -v76, v87, v77
	v_fmac_f32_e32 v86, v90, v82
	v_mul_f32_e32 v89, v81, v85
	v_fma_f32 v92, -v78, v88, v79
	v_fmac_f32_e32 v87, v91, v83
	v_fma_f32 v74, -v74, v86, v75
	v_fma_f32 v93, -v80, v89, v81
	v_fmac_f32_e32 v88, v92, v84
	v_fma_f32 v75, -v76, v87, v77
	v_div_fmas_f32 v74, v74, v82, v86
	s_mov_b64 vcc, s[4:5]
	v_fmac_f32_e32 v89, v93, v85
	v_fma_f32 v76, -v78, v88, v79
	v_div_fixup_f32 v15, v74, v15, v71
	v_div_fmas_f32 v71, v75, v83, v87
	s_mov_b64 vcc, s[6:7]
	v_fma_f32 v77, -v80, v89, v81
	v_div_fixup_f32 v14, v71, v14, v70
	v_div_fmas_f32 v70, v76, v84, v88
	s_mov_b64 vcc, s[8:9]
	v_pk_mul_f32 v[14:15], v[28:29], v[14:15]
	v_div_fmas_f32 v28, v77, v85, v89
	v_div_fixup_f32 v29, v70, v47, v73
	v_div_fixup_f32 v28, v28, v46, v72
	v_pk_mul_f32 v[28:29], v[30:31], v[28:29]
	v_cvt_pk_bf16_f32 v14, v14, v15
	v_cvt_pk_bf16_f32 v15, v28, v29
	v_mov_b32_e32 v134, v14
	v_mov_b32_e32 v135, v15
	v_mbcnt_lo_u32_b32 v138, -1, 0
	v_mbcnt_hi_u32_b32 v138, -1, v138
	v_and_b32_e32 v138, 32, v138
	v_lshrrev_b32_e32 v138, 2, v138
	v_mov_b32_e32 v139, 0
	v_lshl_add_u64 v[136:137], v[4:5], 0, v[138:139]
	v_permlane32_swap_b32_e32 v132, v134
	v_permlane32_swap_b32_e32 v133, v135
	global_store_dwordx4 v[136:137], v[132:135], off
	v_mov_b32_e32 v14, v104
	v_mov_b32_e32 v15, v105
	s_nop 0
	global_load_dwordx4 v[28:31], v13, s[12:13] offset:64
	global_load_dwordx4 v[70:73], v13, s[12:13] offset:96
	v_pk_mul_f32 v[46:47], v[66:67], v[12:13] op_sel_hi:[1,0]
	v_pk_mul_f32 v[66:67], v[68:69], v[12:13] op_sel_hi:[1,0]
	v_lshlrev_b32_e32 v74, 16, v14
	v_and_b32_e32 v75, 0xffff0000, v14
	v_lshlrev_b32_e32 v76, 16, v15
	v_and_b32_e32 v77, 0xffff0000, v15
	v_mul_f32_e32 v14, 0xbfb8aa3b, v74
	v_mul_f32_e32 v15, 0xbfb8aa3b, v75
	v_exp_f32_e32 v14, v14
	v_exp_f32_e32 v15, v15
	v_mul_f32_e32 v68, 0xbfb8aa3b, v76
	v_mul_f32_e32 v69, 0xbfb8aa3b, v77
	v_exp_f32_e32 v68, v68
	v_exp_f32_e32 v69, v69
	v_pk_add_f32 v[14:15], v[14:15], 1.0 op_sel_hi:[1,0]
	s_waitcnt vmcnt(0)
	v_pk_mul_f32 v[30:31], v[66:67], v[30:31]
	v_div_scale_f32 v66, s[4:5], v15, v15, v75
	v_pk_mul_f32 v[28:29], v[46:47], v[28:29]
	v_pk_add_f32 v[46:47], v[68:69], 1.0 op_sel_hi:[1,0]
	v_div_scale_f32 v68, s[4:5], v14, v14, v74
	v_rcp_f32_e32 v82, v66
	v_div_scale_f32 v78, s[6:7], v47, v47, v77
	v_rcp_f32_e32 v83, v68
	v_div_scale_f32 v80, s[8:9], v46, v46, v76
	v_rcp_f32_e32 v84, v78
	v_rcp_f32_e32 v85, v80
	v_fma_f32 v86, -v66, v82, 1.0
	v_div_scale_f32 v67, vcc, v75, v15, v75
	v_fma_f32 v87, -v68, v83, 1.0
	v_fmac_f32_e32 v82, v86, v82
	v_div_scale_f32 v69, s[4:5], v74, v14, v74
	v_fma_f32 v88, -v78, v84, 1.0
	v_fmac_f32_e32 v83, v87, v83
	v_mul_f32_e32 v86, v67, v82
	v_div_scale_f32 v79, s[6:7], v77, v47, v77
	v_fma_f32 v89, -v80, v85, 1.0
	v_fmac_f32_e32 v84, v88, v84
	v_mul_f32_e32 v87, v69, v83
	v_fma_f32 v90, -v66, v86, v67
	v_div_scale_f32 v81, s[8:9], v76, v46, v76
	v_fmac_f32_e32 v85, v89, v85
	v_mul_f32_e32 v88, v79, v84
	v_fma_f32 v91, -v68, v87, v69
	v_fmac_f32_e32 v86, v90, v82
	v_mul_f32_e32 v89, v81, v85
	v_fma_f32 v92, -v78, v88, v79
	v_fmac_f32_e32 v87, v91, v83
	v_fma_f32 v66, -v66, v86, v67
	v_fma_f32 v93, -v80, v89, v81
	v_fmac_f32_e32 v88, v92, v84
	v_fma_f32 v67, -v68, v87, v69
	v_div_fmas_f32 v66, v66, v82, v86
	s_mov_b64 vcc, s[4:5]
	v_fmac_f32_e32 v89, v93, v85
	v_fma_f32 v68, -v78, v88, v79
	v_div_fixup_f32 v15, v66, v15, v75
	v_div_fmas_f32 v66, v67, v83, v87
	s_mov_b64 vcc, s[6:7]
	v_fma_f32 v69, -v80, v89, v81
	v_div_fixup_f32 v14, v66, v14, v74
	v_div_fmas_f32 v66, v68, v84, v88
	s_mov_b64 vcc, s[8:9]
	v_pk_mul_f32 v[14:15], v[28:29], v[14:15]
	v_div_fmas_f32 v28, v69, v85, v89
	v_div_fixup_f32 v29, v66, v47, v77
	v_div_fixup_f32 v28, v28, v46, v76
	v_pk_mul_f32 v[28:29], v[30:31], v[28:29]
	v_cvt_pk_bf16_f32 v14, v14, v15
	v_cvt_pk_bf16_f32 v15, v28, v29
	v_mov_b32_e32 v132, v14
	v_mov_b32_e32 v133, v15
	v_mov_b32_e32 v14, v106
	v_mov_b32_e32 v15, v107
	v_pk_mul_f32 v[30:31], v[62:63], v[12:13] op_sel_hi:[1,0]
	v_pk_mul_f32 v[28:29], v[64:65], v[12:13] op_sel_hi:[1,0]
	s_waitcnt vmcnt(0)
; __device__ __forceinline__ unsigned cvtpk(float lo, float hi) { f32x2 v = {lo, hi}; bf16x2_t b = __builtin_convertvector(v, bf16x2_t); return __builtin_bit_cast(unsigned, b); }
; __device__ __forceinline__ float bf2f(unsigned u16) { return __uint_as_float(u16 << 16); }
; __device__ __forceinline__ float silu(float g) { return g / (1.f + __expf(-g)); }
; template <int MODE>
; __device__ __forceinline__ void attn_unit(const UnitP& P, ALAS char* lds, const float* __restrict__ sub_gain, const int wv0, unsigned& hgen, unsigned* qctr, const int xcd) {
;     ...
;                 for (int d0 = 0; d0 < 4; ++d0)
; #pragma unroll
;                     for (int g = 0; g < 4; ++g) {
;                         const u32x2 gg = *(const u32x2*)(gp + 32 * d0 + 8 * g);
;                         const f32x4 sg = *(const f32x4*)(sub_gain + 32 * d0 + 8 * g + 4 * hi);
;                         const float y0 = o[d0][4 * g + 0] * rn * sg[0] * silu(bf2f(gg.x & 0xffffu)), y1 = o[d0][4 * g + 1] * rn * sg[1] * silu(bf2f(gg.x >> 16));
;                         const float y2 = o[d0][4 * g + 2] * rn * sg[2] * silu(bf2f(gg.y & 0xffffu)), y3 = o[d0][4 * g + 3] * rn * sg[3] * silu(bf2f(gg.y >> 16));
;                         u32x2 w; w.x = cvtpk(y0, y1); w.y = cvtpk(y2, y3);
;                         *(u32x2*)(mp + 32 * d0 + 8 * g) = w;
	v_pk_mul_f32 v[30:31], v[30:31], v[72:73]
	v_pk_mul_f32 v[28:29], v[28:29], v[70:71]
	v_lshlrev_b32_e32 v62, 16, v14
	v_and_b32_e32 v63, 0xffff0000, v14
	v_lshlrev_b32_e32 v64, 16, v15
	v_and_b32_e32 v65, 0xffff0000, v15
	v_mul_f32_e32 v14, 0xbfb8aa3b, v62
	v_mul_f32_e32 v15, 0xbfb8aa3b, v63
	v_exp_f32_e32 v14, v14
	v_exp_f32_e32 v15, v15
	v_mul_f32_e32 v46, 0xbfb8aa3b, v64
	v_mul_f32_e32 v47, 0xbfb8aa3b, v65
	v_exp_f32_e32 v46, v46
	v_exp_f32_e32 v47, v47
	v_pk_add_f32 v[14:15], v[14:15], 1.0 op_sel_hi:[1,0]
	v_pk_add_f32 v[46:47], v[46:47], 1.0 op_sel_hi:[1,0]
	v_div_scale_f32 v66, s[4:5], v15, v15, v63
	v_div_scale_f32 v68, s[4:5], v14, v14, v62
	v_rcp_f32_e32 v74, v66
	v_div_scale_f32 v70, s[6:7], v47, v47, v65
	v_rcp_f32_e32 v75, v68
	v_div_scale_f32 v72, s[8:9], v46, v46, v64
	v_rcp_f32_e32 v76, v70
	v_rcp_f32_e32 v77, v72
	v_fma_f32 v78, -v66, v74, 1.0
	v_div_scale_f32 v67, vcc, v63, v15, v63
	v_fma_f32 v79, -v68, v75, 1.0
	v_fmac_f32_e32 v74, v78, v74
	v_div_scale_f32 v69, s[4:5], v62, v14, v62
	v_fma_f32 v80, -v70, v76, 1.0
	v_fmac_f32_e32 v75, v79, v75
	v_mul_f32_e32 v78, v67, v74
	v_div_scale_f32 v71, s[6:7], v65, v47, v65
	v_fma_f32 v81, -v72, v77, 1.0
	v_fmac_f32_e32 v76, v80, v76
	v_mul_f32_e32 v79, v69, v75
	v_fma_f32 v82, -v66, v78, v67
	v_div_scale_f32 v73, s[8:9], v64, v46, v64
	v_fmac_f32_e32 v77, v81, v77
	v_mul_f32_e32 v80, v71, v76
	v_fma_f32 v83, -v68, v79, v69
	v_fmac_f32_e32 v78, v82, v74
	v_mul_f32_e32 v81, v73, v77
	v_fma_f32 v84, -v70, v80, v71
	v_fmac_f32_e32 v79, v83, v75
	v_fma_f32 v66, -v66, v78, v67
	v_fma_f32 v85, -v72, v81, v73
	v_fmac_f32_e32 v80, v84, v76
	v_fma_f32 v67, -v68, v79, v69
	v_div_fmas_f32 v66, v66, v74, v78
	s_mov_b64 vcc, s[4:5]
	v_fmac_f32_e32 v81, v85, v77
	v_fma_f32 v68, -v70, v80, v71
	v_div_fixup_f32 v15, v66, v15, v63
	v_div_fmas_f32 v63, v67, v75, v79
	s_mov_b64 vcc, s[6:7]
	v_fma_f32 v69, -v72, v81, v73
	v_div_fixup_f32 v14, v63, v14, v62
	v_div_fmas_f32 v62, v68, v76, v80
	s_mov_b64 vcc, s[8:9]
	v_pk_mul_f32 v[14:15], v[28:29], v[14:15]
	v_div_fmas_f32 v28, v69, v77, v81
	v_div_fixup_f32 v29, v62, v47, v65
	v_div_fixup_f32 v28, v28, v46, v64
	v_pk_mul_f32 v[28:29], v[30:31], v[28:29]
	v_cvt_pk_bf16_f32 v14, v14, v15
	v_cvt_pk_bf16_f32 v15, v28, v29
	v_mov_b32_e32 v134, v14
	v_mov_b32_e32 v135, v15
	s_nop 1
	v_permlane32_swap_b32_e32 v132, v134
	v_permlane32_swap_b32_e32 v133, v135
	global_store_dwordx4 v[136:137], v[132:135], off offset:32
	v_mov_b32_e32 v14, v108
	v_mov_b32_e32 v15, v109
	s_nop 0
	global_load_dwordx4 v[28:31], v13, s[12:13] offset:128
	global_load_dwordx4 v[62:65], v13, s[12:13] offset:160
	v_pk_mul_f32 v[46:47], v[58:59], v[12:13] op_sel_hi:[1,0]
	v_pk_mul_f32 v[58:59], v[60:61], v[12:13] op_sel_hi:[1,0]
	v_lshlrev_b32_e32 v66, 16, v14
	v_and_b32_e32 v67, 0xffff0000, v14
	v_lshlrev_b32_e32 v68, 16, v15
	v_and_b32_e32 v69, 0xffff0000, v15
	v_mul_f32_e32 v14, 0xbfb8aa3b, v66
	v_mul_f32_e32 v15, 0xbfb8aa3b, v67
	v_exp_f32_e32 v14, v14
	v_exp_f32_e32 v15, v15
	v_mul_f32_e32 v60, 0xbfb8aa3b, v68
	v_mul_f32_e32 v61, 0xbfb8aa3b, v69
	v_exp_f32_e32 v60, v60
	v_exp_f32_e32 v61, v61
	v_pk_add_f32 v[14:15], v[14:15], 1.0 op_sel_hi:[1,0]
	s_waitcnt vmcnt(0)
	v_pk_mul_f32 v[30:31], v[58:59], v[30:31]
	v_div_scale_f32 v58, s[4:5], v15, v15, v67
	v_pk_mul_f32 v[28:29], v[46:47], v[28:29]
	v_pk_add_f32 v[46:47], v[60:61], 1.0 op_sel_hi:[1,0]
	v_div_scale_f32 v60, s[4:5], v14, v14, v66
	v_rcp_f32_e32 v74, v58
	v_div_scale_f32 v70, s[6:7], v47, v47, v69
	v_rcp_f32_e32 v75, v60
	v_div_scale_f32 v72, s[8:9], v46, v46, v68
	v_rcp_f32_e32 v76, v70
	v_rcp_f32_e32 v77, v72
	v_fma_f32 v78, -v58, v74, 1.0
	v_div_scale_f32 v59, vcc, v67, v15, v67
	v_fma_f32 v79, -v60, v75, 1.0
	v_fmac_f32_e32 v74, v78, v74
	v_div_scale_f32 v61, s[4:5], v66, v14, v66
	v_fma_f32 v80, -v70, v76, 1.0
	v_fmac_f32_e32 v75, v79, v75
	v_mul_f32_e32 v78, v59, v74
	v_div_scale_f32 v71, s[6:7], v69, v47, v69
	v_fma_f32 v81, -v72, v77, 1.0
	v_fmac_f32_e32 v76, v80, v76
	v_mul_f32_e32 v79, v61, v75
	v_fma_f32 v82, -v58, v78, v59
	v_div_scale_f32 v73, s[8:9], v68, v46, v68
	v_fmac_f32_e32 v77, v81, v77
	v_mul_f32_e32 v80, v71, v76
	v_fma_f32 v83, -v60, v79, v61
	v_fmac_f32_e32 v78, v82, v74
	v_mul_f32_e32 v81, v73, v77
	v_fma_f32 v84, -v70, v80, v71
	v_fmac_f32_e32 v79, v83, v75
	v_fma_f32 v58, -v58, v78, v59
	v_fma_f32 v85, -v72, v81, v73
	v_fmac_f32_e32 v80, v84, v76
	v_fma_f32 v59, -v60, v79, v61
	v_div_fmas_f32 v58, v58, v74, v78
	s_mov_b64 vcc, s[4:5]
	v_fmac_f32_e32 v81, v85, v77
	v_fma_f32 v60, -v70, v80, v71
	v_div_fixup_f32 v15, v58, v15, v67
	v_div_fmas_f32 v58, v59, v75, v79
	s_mov_b64 vcc, s[6:7]
	v_fma_f32 v61, -v72, v81, v73
	v_div_fixup_f32 v14, v58, v14, v66
	v_div_fmas_f32 v58, v60, v76, v80
	s_mov_b64 vcc, s[8:9]
	v_pk_mul_f32 v[14:15], v[28:29], v[14:15]
	v_div_fmas_f32 v28, v61, v77, v81
	v_div_fixup_f32 v29, v58, v47, v69
	v_div_fixup_f32 v28, v28, v46, v68
	v_pk_mul_f32 v[28:29], v[30:31], v[28:29]
	v_cvt_pk_bf16_f32 v14, v14, v15
	v_cvt_pk_bf16_f32 v15, v28, v29
	v_mov_b32_e32 v132, v14
	v_mov_b32_e32 v133, v15
	v_mov_b32_e32 v14, v110
	v_mov_b32_e32 v15, v111
	v_pk_mul_f32 v[30:31], v[54:55], v[12:13] op_sel_hi:[1,0]
	v_pk_mul_f32 v[28:29], v[56:57], v[12:13] op_sel_hi:[1,0]
	s_waitcnt vmcnt(0)
; __device__ __forceinline__ unsigned cvtpk(float lo, float hi) { f32x2 v = {lo, hi}; bf16x2_t b = __builtin_convertvector(v, bf16x2_t); return __builtin_bit_cast(unsigned, b); }
; __device__ __forceinline__ float bf2f(unsigned u16) { return __uint_as_float(u16 << 16); }
; __device__ __forceinline__ float silu(float g) { return g / (1.f + __expf(-g)); }
; template <int MODE>
; __device__ __forceinline__ void attn_unit(const UnitP& P, ALAS char* lds, const float* __restrict__ sub_gain, const int wv0, unsigned& hgen, unsigned* qctr, const int xcd) {
;     ...
;                 for (int d0 = 0; d0 < 4; ++d0)
; #pragma unroll
;                     for (int g = 0; g < 4; ++g) {
;                         const u32x2 gg = *(const u32x2*)(gp + 32 * d0 + 8 * g);
;                         const f32x4 sg = *(const f32x4*)(sub_gain + 32 * d0 + 8 * g + 4 * hi);
;                         const float y0 = o[d0][4 * g + 0] * rn * sg[0] * silu(bf2f(gg.x & 0xffffu)), y1 = o[d0][4 * g + 1] * rn * sg[1] * silu(bf2f(gg.x >> 16));
;                         const float y2 = o[d0][4 * g + 2] * rn * sg[2] * silu(bf2f(gg.y & 0xffffu)), y3 = o[d0][4 * g + 3] * rn * sg[3] * silu(bf2f(gg.y >> 16));
;                         u32x2 w; w.x = cvtpk(y0, y1); w.y = cvtpk(y2, y3);
;                         *(u32x2*)(mp + 32 * d0 + 8 * g) = w;
	v_pk_mul_f32 v[30:31], v[30:31], v[64:65]
	v_pk_mul_f32 v[28:29], v[28:29], v[62:63]
	v_lshlrev_b32_e32 v54, 16, v14
	v_and_b32_e32 v55, 0xffff0000, v14
	v_lshlrev_b32_e32 v56, 16, v15
	v_and_b32_e32 v57, 0xffff0000, v15
	v_mul_f32_e32 v14, 0xbfb8aa3b, v54
	v_mul_f32_e32 v15, 0xbfb8aa3b, v55
	v_exp_f32_e32 v14, v14
	v_exp_f32_e32 v15, v15
	v_mul_f32_e32 v46, 0xbfb8aa3b, v56
	v_mul_f32_e32 v47, 0xbfb8aa3b, v57
	v_exp_f32_e32 v46, v46
	v_exp_f32_e32 v47, v47
	v_pk_add_f32 v[14:15], v[14:15], 1.0 op_sel_hi:[1,0]
	v_pk_add_f32 v[46:47], v[46:47], 1.0 op_sel_hi:[1,0]
	v_div_scale_f32 v58, s[4:5], v15, v15, v55
	v_div_scale_f32 v60, s[4:5], v14, v14, v54
	v_rcp_f32_e32 v66, v58
	v_div_scale_f32 v62, s[6:7], v47, v47, v57
	v_rcp_f32_e32 v67, v60
	v_div_scale_f32 v64, s[8:9], v46, v46, v56
	v_rcp_f32_e32 v68, v62
	v_rcp_f32_e32 v69, v64
	v_fma_f32 v70, -v58, v66, 1.0
	v_div_scale_f32 v59, vcc, v55, v15, v55
	v_fma_f32 v71, -v60, v67, 1.0
	v_fmac_f32_e32 v66, v70, v66
	v_div_scale_f32 v61, s[4:5], v54, v14, v54
	v_fma_f32 v72, -v62, v68, 1.0
	v_fmac_f32_e32 v67, v71, v67
	v_mul_f32_e32 v70, v59, v66
	v_div_scale_f32 v63, s[6:7], v57, v47, v57
	v_fma_f32 v73, -v64, v69, 1.0
	v_fmac_f32_e32 v68, v72, v68
	v_mul_f32_e32 v71, v61, v67
	v_fma_f32 v74, -v58, v70, v59
	v_div_scale_f32 v65, s[8:9], v56, v46, v56
	v_fmac_f32_e32 v69, v73, v69
	v_mul_f32_e32 v72, v63, v68
	v_fma_f32 v75, -v60, v71, v61
	v_fmac_f32_e32 v70, v74, v66
	v_mul_f32_e32 v73, v65, v69
	v_fma_f32 v76, -v62, v72, v63
	v_fmac_f32_e32 v71, v75, v67
	v_fma_f32 v58, -v58, v70, v59
	v_fma_f32 v77, -v64, v73, v65
	v_fmac_f32_e32 v72, v76, v68
	v_fma_f32 v59, -v60, v71, v61
	v_div_fmas_f32 v58, v58, v66, v70
	s_mov_b64 vcc, s[4:5]
	v_fmac_f32_e32 v73, v77, v69
	v_fma_f32 v60, -v62, v72, v63
	v_div_fixup_f32 v15, v58, v15, v55
	v_div_fmas_f32 v55, v59, v67, v71
	s_mov_b64 vcc, s[6:7]
	v_fma_f32 v61, -v64, v73, v65
	v_div_fixup_f32 v14, v55, v14, v54
	v_div_fmas_f32 v54, v60, v68, v72
	s_mov_b64 vcc, s[8:9]
	v_pk_mul_f32 v[14:15], v[28:29], v[14:15]
	v_div_fmas_f32 v28, v61, v69, v73
	v_div_fixup_f32 v29, v54, v47, v57
	v_div_fixup_f32 v28, v28, v46, v56
	v_pk_mul_f32 v[28:29], v[30:31], v[28:29]
	v_cvt_pk_bf16_f32 v14, v14, v15
	v_cvt_pk_bf16_f32 v15, v28, v29
	v_mov_b32_e32 v134, v14
	v_mov_b32_e32 v135, v15
	s_nop 1
	v_permlane32_swap_b32_e32 v132, v134
	v_permlane32_swap_b32_e32 v133, v135
	global_store_dwordx4 v[136:137], v[132:135], off offset:64
	v_mov_b32_e32 v14, v112
	v_mov_b32_e32 v15, v113
	s_nop 0
	global_load_dwordx4 v[28:31], v13, s[12:13] offset:192
	global_load_dwordx4 v[54:57], v13, s[12:13] offset:224
	v_pk_mul_f32 v[46:47], v[50:51], v[12:13] op_sel_hi:[1,0]
	v_pk_mul_f32 v[50:51], v[52:53], v[12:13] op_sel_hi:[1,0]
	v_lshlrev_b32_e32 v58, 16, v14
	v_and_b32_e32 v59, 0xffff0000, v14
	v_lshlrev_b32_e32 v60, 16, v15
	v_and_b32_e32 v61, 0xffff0000, v15
	v_mul_f32_e32 v14, 0xbfb8aa3b, v58
	v_mul_f32_e32 v15, 0xbfb8aa3b, v59
	v_exp_f32_e32 v14, v14
	v_exp_f32_e32 v15, v15
	v_mul_f32_e32 v52, 0xbfb8aa3b, v60
	v_mul_f32_e32 v53, 0xbfb8aa3b, v61
	v_exp_f32_e32 v52, v52
	v_exp_f32_e32 v53, v53
	v_pk_add_f32 v[14:15], v[14:15], 1.0 op_sel_hi:[1,0]
	s_waitcnt vmcnt(0)
	v_pk_mul_f32 v[30:31], v[50:51], v[30:31]
	v_div_scale_f32 v50, s[4:5], v15, v15, v59
	v_pk_mul_f32 v[28:29], v[46:47], v[28:29]
	v_pk_add_f32 v[46:47], v[52:53], 1.0 op_sel_hi:[1,0]
	v_div_scale_f32 v52, s[4:5], v14, v14, v58
	v_rcp_f32_e32 v66, v50
	v_div_scale_f32 v62, s[6:7], v47, v47, v61
	v_rcp_f32_e32 v67, v52
	v_div_scale_f32 v64, s[8:9], v46, v46, v60
	v_rcp_f32_e32 v68, v62
	v_rcp_f32_e32 v69, v64
	v_fma_f32 v70, -v50, v66, 1.0
	v_div_scale_f32 v51, vcc, v59, v15, v59
	v_fma_f32 v71, -v52, v67, 1.0
	v_fmac_f32_e32 v66, v70, v66
	v_div_scale_f32 v53, s[4:5], v58, v14, v58
	v_fma_f32 v72, -v62, v68, 1.0
	v_fmac_f32_e32 v67, v71, v67
	v_mul_f32_e32 v70, v51, v66
	v_div_scale_f32 v63, s[6:7], v61, v47, v61
	v_fma_f32 v73, -v64, v69, 1.0
	v_fmac_f32_e32 v68, v72, v68
	v_mul_f32_e32 v71, v53, v67
	v_fma_f32 v74, -v50, v70, v51
	v_div_scale_f32 v65, s[8:9], v60, v46, v60
	v_fmac_f32_e32 v69, v73, v69
	v_mul_f32_e32 v72, v63, v68
	v_fma_f32 v75, -v52, v71, v53
	v_fmac_f32_e32 v70, v74, v66
	v_mul_f32_e32 v73, v65, v69
	v_fma_f32 v76, -v62, v72, v63
	v_fmac_f32_e32 v71, v75, v67
	v_fma_f32 v50, -v50, v70, v51
	v_fma_f32 v77, -v64, v73, v65
	v_fmac_f32_e32 v72, v76, v68
	v_fma_f32 v51, -v52, v71, v53
	v_div_fmas_f32 v50, v50, v66, v70
	s_mov_b64 vcc, s[4:5]
	v_fmac_f32_e32 v73, v77, v69
	v_fma_f32 v52, -v62, v72, v63
	v_div_fixup_f32 v15, v50, v15, v59
	v_div_fmas_f32 v50, v51, v67, v71
	s_mov_b64 vcc, s[6:7]
	v_fma_f32 v53, -v64, v73, v65
	v_div_fixup_f32 v14, v50, v14, v58
	v_div_fmas_f32 v50, v52, v68, v72
	s_mov_b64 vcc, s[8:9]
	v_pk_mul_f32 v[14:15], v[28:29], v[14:15]
	v_div_fmas_f32 v28, v53, v69, v73
	v_div_fixup_f32 v29, v50, v47, v61
	v_div_fixup_f32 v28, v28, v46, v60
	v_pk_mul_f32 v[28:29], v[30:31], v[28:29]
	v_cvt_pk_bf16_f32 v14, v14, v15
	v_cvt_pk_bf16_f32 v15, v28, v29
	v_mov_b32_e32 v132, v14
	v_mov_b32_e32 v133, v15
	v_mov_b32_e32 v14, v114
	v_mov_b32_e32 v15, v115
	v_pk_mul_f32 v[28:29], v[48:49], v[12:13] op_sel_hi:[1,0]
	v_pk_mul_f32 v[30:31], v[44:45], v[12:13] op_sel_hi:[1,0]
	s_waitcnt vmcnt(0)
; __device__ __forceinline__ unsigned cvtpk(float lo, float hi) { f32x2 v = {lo, hi}; bf16x2_t b = __builtin_convertvector(v, bf16x2_t); return __builtin_bit_cast(unsigned, b); }
; __device__ __forceinline__ float bf2f(unsigned u16) { return __uint_as_float(u16 << 16); }
; __device__ __forceinline__ float silu(float g) { return g / (1.f + __expf(-g)); }
; template <int MODE>
; __device__ __forceinline__ void attn_unit(const UnitP& P, ALAS char* lds, const float* __restrict__ sub_gain, const int wv0, unsigned& hgen, unsigned* qctr, const int xcd) {
;     ...
;                 for (int d0 = 0; d0 < 4; ++d0)
; #pragma unroll
;                     for (int g = 0; g < 4; ++g) {
;                         const u32x2 gg = *(const u32x2*)(gp + 32 * d0 + 8 * g);
;                         const f32x4 sg = *(const f32x4*)(sub_gain + 32 * d0 + 8 * g + 4 * hi);
;                         const float y0 = o[d0][4 * g + 0] * rn * sg[0] * silu(bf2f(gg.x & 0xffffu)), y1 = o[d0][4 * g + 1] * rn * sg[1] * silu(bf2f(gg.x >> 16));
;                         const float y2 = o[d0][4 * g + 2] * rn * sg[2] * silu(bf2f(gg.y & 0xffffu)), y3 = o[d0][4 * g + 3] * rn * sg[3] * silu(bf2f(gg.y >> 16));
;                         u32x2 w; w.x = cvtpk(y0, y1); w.y = cvtpk(y2, y3);
;                         *(u32x2*)(mp + 32 * d0 + 8 * g) = w;
	v_pk_mul_f32 v[28:29], v[28:29], v[54:55]
	v_pk_mul_f32 v[30:31], v[30:31], v[56:57]
	v_lshlrev_b32_e32 v46, 16, v14
	v_and_b32_e32 v47, 0xffff0000, v14
	v_lshlrev_b32_e32 v48, 16, v15
	v_and_b32_e32 v49, 0xffff0000, v15
	v_mul_f32_e32 v14, 0xbfb8aa3b, v46
	v_mul_f32_e32 v15, 0xbfb8aa3b, v47
	v_exp_f32_e32 v14, v14
	v_exp_f32_e32 v15, v15
	v_mul_f32_e32 v44, 0xbfb8aa3b, v48
	v_mul_f32_e32 v45, 0xbfb8aa3b, v49
	v_exp_f32_e32 v44, v44
	v_exp_f32_e32 v45, v45
	v_pk_add_f32 v[14:15], v[14:15], 1.0 op_sel_hi:[1,0]
	v_pk_add_f32 v[44:45], v[44:45], 1.0 op_sel_hi:[1,0]
	v_div_scale_f32 v50, s[4:5], v15, v15, v47
	v_div_scale_f32 v52, s[4:5], v14, v14, v46
	v_rcp_f32_e32 v58, v50
	v_div_scale_f32 v54, s[6:7], v45, v45, v49
	v_rcp_f32_e32 v59, v52
	v_div_scale_f32 v56, s[8:9], v44, v44, v48
	v_rcp_f32_e32 v60, v54
	v_rcp_f32_e32 v61, v56
	v_fma_f32 v62, -v50, v58, 1.0
	v_div_scale_f32 v51, vcc, v47, v15, v47
	v_fma_f32 v63, -v52, v59, 1.0
	v_fmac_f32_e32 v58, v62, v58
	v_div_scale_f32 v53, s[4:5], v46, v14, v46
	v_fma_f32 v64, -v54, v60, 1.0
	v_fmac_f32_e32 v59, v63, v59
	v_mul_f32_e32 v62, v51, v58
	v_div_scale_f32 v55, s[6:7], v49, v45, v49
	v_fma_f32 v65, -v56, v61, 1.0
	v_fmac_f32_e32 v60, v64, v60
	v_mul_f32_e32 v63, v53, v59
	v_fma_f32 v66, -v50, v62, v51
	v_div_scale_f32 v57, s[8:9], v48, v44, v48
	v_fmac_f32_e32 v61, v65, v61
	v_mul_f32_e32 v64, v55, v60
	v_fma_f32 v67, -v52, v63, v53
	v_fmac_f32_e32 v62, v66, v58
	v_mul_f32_e32 v65, v57, v61
	v_fma_f32 v68, -v54, v64, v55
	v_fmac_f32_e32 v63, v67, v59
	v_fma_f32 v50, -v50, v62, v51
	v_fma_f32 v69, -v56, v65, v57
	v_fmac_f32_e32 v64, v68, v60
	v_fma_f32 v51, -v52, v63, v53
	v_div_fmas_f32 v50, v50, v58, v62
	s_mov_b64 vcc, s[4:5]
	v_fmac_f32_e32 v65, v69, v61
	v_fma_f32 v52, -v54, v64, v55
	v_div_fixup_f32 v15, v50, v15, v47
	v_div_fmas_f32 v47, v51, v59, v63
	s_mov_b64 vcc, s[6:7]
	v_fma_f32 v53, -v56, v65, v57
	v_div_fixup_f32 v14, v47, v14, v46
	v_div_fmas_f32 v46, v52, v60, v64
	s_mov_b64 vcc, s[8:9]
	v_pk_mul_f32 v[14:15], v[28:29], v[14:15]
	v_div_fmas_f32 v28, v53, v61, v65
	v_div_fixup_f32 v29, v46, v45, v49
	v_div_fixup_f32 v28, v28, v44, v48
	v_pk_mul_f32 v[28:29], v[30:31], v[28:29]
	v_cvt_pk_bf16_f32 v14, v14, v15
	v_cvt_pk_bf16_f32 v15, v28, v29
	v_mov_b32_e32 v134, v14
	v_mov_b32_e32 v135, v15
	s_nop 1
	v_permlane32_swap_b32_e32 v132, v134
	v_permlane32_swap_b32_e32 v133, v135
	global_store_dwordx4 v[136:137], v[132:135], off offset:96
	v_mov_b32_e32 v14, v116
	v_mov_b32_e32 v15, v117
	s_nop 0
	global_load_dwordx4 v[28:31], v13, s[12:13] offset:256
	global_load_dwordx4 v[44:47], v13, s[12:13] offset:288
	v_lshlrev_b32_e32 v50, 16, v14
	v_and_b32_e32 v51, 0xffff0000, v14
	v_lshlrev_b32_e32 v52, 16, v15
	v_and_b32_e32 v53, 0xffff0000, v15
	v_mul_f32_e32 v14, 0xbfb8aa3b, v50
	v_mul_f32_e32 v15, 0xbfb8aa3b, v51
	v_exp_f32_e32 v14, v14
	v_exp_f32_e32 v15, v15
	v_mul_f32_e32 v48, 0xbfb8aa3b, v52
	v_mul_f32_e32 v49, 0xbfb8aa3b, v53
	v_exp_f32_e32 v48, v48
	v_exp_f32_e32 v49, v49
	v_pk_add_f32 v[14:15], v[14:15], 1.0 op_sel_hi:[1,0]
	s_waitcnt vmcnt(0)
	v_pk_mul_f32 v[30:31], v[42:43], v[30:31]
	v_div_scale_f32 v42, s[4:5], v15, v15, v51
	v_pk_mul_f32 v[28:29], v[40:41], v[28:29]
	v_pk_add_f32 v[40:41], v[48:49], 1.0 op_sel_hi:[1,0]
	v_div_scale_f32 v48, s[4:5], v14, v14, v50
	v_rcp_f32_e32 v58, v42
	v_div_scale_f32 v54, s[6:7], v41, v41, v53
	v_rcp_f32_e32 v59, v48
	v_div_scale_f32 v56, s[8:9], v40, v40, v52
	v_rcp_f32_e32 v60, v54
	v_rcp_f32_e32 v61, v56
	v_fma_f32 v62, -v42, v58, 1.0
	v_div_scale_f32 v43, vcc, v51, v15, v51
	v_fma_f32 v63, -v48, v59, 1.0
	v_fmac_f32_e32 v58, v62, v58
	v_div_scale_f32 v49, s[4:5], v50, v14, v50
	v_fma_f32 v64, -v54, v60, 1.0
	v_fmac_f32_e32 v59, v63, v59
	v_mul_f32_e32 v62, v43, v58
	v_div_scale_f32 v55, s[6:7], v53, v41, v53
	v_fma_f32 v65, -v56, v61, 1.0
	v_fmac_f32_e32 v60, v64, v60
	v_mul_f32_e32 v63, v49, v59
	v_fma_f32 v66, -v42, v62, v43
	v_div_scale_f32 v57, s[8:9], v52, v40, v52
	v_fmac_f32_e32 v61, v65, v61
	v_mul_f32_e32 v64, v55, v60
	v_fma_f32 v67, -v48, v63, v49
	v_fmac_f32_e32 v62, v66, v58
	v_mul_f32_e32 v65, v57, v61
	v_fma_f32 v68, -v54, v64, v55
	v_fmac_f32_e32 v63, v67, v59
	v_fma_f32 v42, -v42, v62, v43
	v_fma_f32 v69, -v56, v65, v57
	v_fmac_f32_e32 v64, v68, v60
	v_fma_f32 v43, -v48, v63, v49
	v_div_fmas_f32 v42, v42, v58, v62
	s_mov_b64 vcc, s[4:5]
	v_fmac_f32_e32 v65, v69, v61
	v_fma_f32 v48, -v54, v64, v55
	v_div_fixup_f32 v15, v42, v15, v51
	v_div_fmas_f32 v42, v43, v59, v63
	s_mov_b64 vcc, s[6:7]
	v_fma_f32 v49, -v56, v65, v57
	v_div_fixup_f32 v14, v42, v14, v50
	v_div_fmas_f32 v42, v48, v60, v64
	s_mov_b64 vcc, s[8:9]
	v_pk_mul_f32 v[14:15], v[28:29], v[14:15]
	v_div_fmas_f32 v28, v49, v61, v65
	v_div_fixup_f32 v29, v42, v41, v53
	v_div_fixup_f32 v28, v28, v40, v52
	v_pk_mul_f32 v[28:29], v[30:31], v[28:29]
	v_cvt_pk_bf16_f32 v14, v14, v15
	v_cvt_pk_bf16_f32 v15, v28, v29
	v_mov_b32_e32 v132, v14
	v_mov_b32_e32 v133, v15
	v_mov_b32_e32 v14, v118
	v_mov_b32_e32 v15, v119
	v_pk_mul_f32 v[28:29], v[38:39], v[12:13] op_sel_hi:[1,0]
	v_pk_mul_f32 v[30:31], v[36:37], v[12:13] op_sel_hi:[1,0]
	s_waitcnt vmcnt(0)
; __device__ __forceinline__ unsigned cvtpk(float lo, float hi) { f32x2 v = {lo, hi}; bf16x2_t b = __builtin_convertvector(v, bf16x2_t); return __builtin_bit_cast(unsigned, b); }
; __device__ __forceinline__ float bf2f(unsigned u16) { return __uint_as_float(u16 << 16); }
; __device__ __forceinline__ float silu(float g) { return g / (1.f + __expf(-g)); }
; template <int MODE>
; __device__ __forceinline__ void attn_unit(const UnitP& P, ALAS char* lds, const float* __restrict__ sub_gain, const int wv0, unsigned& hgen, unsigned* qctr, const int xcd) {
;     ...
;                 for (int d0 = 0; d0 < 4; ++d0)
; #pragma unroll
;                     for (int g = 0; g < 4; ++g) {
;                         const u32x2 gg = *(const u32x2*)(gp + 32 * d0 + 8 * g);
;                         const f32x4 sg = *(const f32x4*)(sub_gain + 32 * d0 + 8 * g + 4 * hi);
;                         const float y0 = o[d0][4 * g + 0] * rn * sg[0] * silu(bf2f(gg.x & 0xffffu)), y1 = o[d0][4 * g + 1] * rn * sg[1] * silu(bf2f(gg.x >> 16));
;                         const float y2 = o[d0][4 * g + 2] * rn * sg[2] * silu(bf2f(gg.y & 0xffffu)), y3 = o[d0][4 * g + 3] * rn * sg[3] * silu(bf2f(gg.y >> 16));
;                         u32x2 w; w.x = cvtpk(y0, y1); w.y = cvtpk(y2, y3);
;                         *(u32x2*)(mp + 32 * d0 + 8 * g) = w;
	v_pk_mul_f32 v[28:29], v[28:29], v[44:45]
	v_pk_mul_f32 v[30:31], v[30:31], v[46:47]
	v_lshlrev_b32_e32 v38, 16, v14
	v_and_b32_e32 v39, 0xffff0000, v14
	v_lshlrev_b32_e32 v40, 16, v15
	v_and_b32_e32 v41, 0xffff0000, v15
	v_mul_f32_e32 v14, 0xbfb8aa3b, v38
	v_mul_f32_e32 v15, 0xbfb8aa3b, v39
	v_exp_f32_e32 v14, v14
	v_exp_f32_e32 v15, v15
	v_mul_f32_e32 v36, 0xbfb8aa3b, v40
	v_mul_f32_e32 v37, 0xbfb8aa3b, v41
	v_exp_f32_e32 v36, v36
	v_exp_f32_e32 v37, v37
	v_pk_add_f32 v[14:15], v[14:15], 1.0 op_sel_hi:[1,0]
	v_pk_add_f32 v[36:37], v[36:37], 1.0 op_sel_hi:[1,0]
	v_div_scale_f32 v42, s[4:5], v15, v15, v39
	v_div_scale_f32 v44, s[4:5], v14, v14, v38
	v_rcp_f32_e32 v50, v42
	v_div_scale_f32 v46, s[6:7], v37, v37, v41
	v_rcp_f32_e32 v51, v44
	v_div_scale_f32 v48, s[8:9], v36, v36, v40
	v_rcp_f32_e32 v52, v46
	v_rcp_f32_e32 v53, v48
	v_fma_f32 v54, -v42, v50, 1.0
	v_div_scale_f32 v43, vcc, v39, v15, v39
	v_fma_f32 v55, -v44, v51, 1.0
	v_fmac_f32_e32 v50, v54, v50
	v_div_scale_f32 v45, s[4:5], v38, v14, v38
	v_fma_f32 v56, -v46, v52, 1.0
	v_fmac_f32_e32 v51, v55, v51
	v_mul_f32_e32 v54, v43, v50
	v_div_scale_f32 v47, s[6:7], v41, v37, v41
	v_fma_f32 v57, -v48, v53, 1.0
	v_fmac_f32_e32 v52, v56, v52
	v_mul_f32_e32 v55, v45, v51
	v_fma_f32 v58, -v42, v54, v43
	v_div_scale_f32 v49, s[8:9], v40, v36, v40
	v_fmac_f32_e32 v53, v57, v53
	v_mul_f32_e32 v56, v47, v52
	v_fma_f32 v59, -v44, v55, v45
	v_fmac_f32_e32 v54, v58, v50
	v_mul_f32_e32 v57, v49, v53
	v_fma_f32 v60, -v46, v56, v47
	v_fmac_f32_e32 v55, v59, v51
	v_fma_f32 v42, -v42, v54, v43
	v_fma_f32 v61, -v48, v57, v49
	v_fmac_f32_e32 v56, v60, v52
	v_fma_f32 v43, -v44, v55, v45
	v_div_fmas_f32 v42, v42, v50, v54
	s_mov_b64 vcc, s[4:5]
	v_fmac_f32_e32 v57, v61, v53
	v_fma_f32 v44, -v46, v56, v47
	v_div_fixup_f32 v15, v42, v15, v39
	v_div_fmas_f32 v39, v43, v51, v55
	s_mov_b64 vcc, s[6:7]
	v_fma_f32 v45, -v48, v57, v49
	v_div_fixup_f32 v14, v39, v14, v38
	v_div_fmas_f32 v38, v44, v52, v56
	s_mov_b64 vcc, s[8:9]
	v_pk_mul_f32 v[14:15], v[28:29], v[14:15]
	v_div_fmas_f32 v28, v45, v53, v57
	v_div_fixup_f32 v29, v38, v37, v41
	v_div_fixup_f32 v28, v28, v36, v40
	v_pk_mul_f32 v[28:29], v[30:31], v[28:29]
	v_cvt_pk_bf16_f32 v14, v14, v15
	v_cvt_pk_bf16_f32 v15, v28, v29
	v_mov_b32_e32 v134, v14
	v_mov_b32_e32 v135, v15
	s_nop 1
	v_permlane32_swap_b32_e32 v132, v134
	v_permlane32_swap_b32_e32 v133, v135
	global_store_dwordx4 v[136:137], v[132:135], off offset:128
	v_mov_b32_e32 v14, v120
	v_mov_b32_e32 v15, v121
	s_nop 0
	global_load_dwordx4 v[28:31], v13, s[12:13] offset:320
	global_load_dwordx4 v[36:39], v13, s[12:13] offset:352
	v_lshlrev_b32_e32 v42, 16, v14
	v_and_b32_e32 v43, 0xffff0000, v14
	v_lshlrev_b32_e32 v44, 16, v15
	v_and_b32_e32 v45, 0xffff0000, v15
	v_mul_f32_e32 v14, 0xbfb8aa3b, v42
	v_mul_f32_e32 v15, 0xbfb8aa3b, v43
	v_exp_f32_e32 v14, v14
	v_exp_f32_e32 v15, v15
	v_mul_f32_e32 v40, 0xbfb8aa3b, v44
	v_mul_f32_e32 v41, 0xbfb8aa3b, v45
	v_exp_f32_e32 v40, v40
	v_exp_f32_e32 v41, v41
	v_pk_add_f32 v[14:15], v[14:15], 1.0 op_sel_hi:[1,0]
	s_waitcnt vmcnt(0)
	v_pk_mul_f32 v[30:31], v[34:35], v[30:31]
	v_div_scale_f32 v34, s[4:5], v15, v15, v43
	v_pk_mul_f32 v[28:29], v[32:33], v[28:29]
	v_pk_add_f32 v[32:33], v[40:41], 1.0 op_sel_hi:[1,0]
	v_div_scale_f32 v40, s[4:5], v14, v14, v42
	v_rcp_f32_e32 v50, v34
	v_div_scale_f32 v46, s[6:7], v33, v33, v45
	v_rcp_f32_e32 v51, v40
	v_div_scale_f32 v48, s[8:9], v32, v32, v44
	v_rcp_f32_e32 v52, v46
	v_rcp_f32_e32 v53, v48
	v_fma_f32 v54, -v34, v50, 1.0
	v_div_scale_f32 v35, vcc, v43, v15, v43
	v_fma_f32 v55, -v40, v51, 1.0
	v_fmac_f32_e32 v50, v54, v50
	v_div_scale_f32 v41, s[4:5], v42, v14, v42
	v_fma_f32 v56, -v46, v52, 1.0
	v_fmac_f32_e32 v51, v55, v51
	v_mul_f32_e32 v54, v35, v50
	v_div_scale_f32 v47, s[6:7], v45, v33, v45
	v_fma_f32 v57, -v48, v53, 1.0
	v_fmac_f32_e32 v52, v56, v52
	v_mul_f32_e32 v55, v41, v51
	v_fma_f32 v58, -v34, v54, v35
	v_div_scale_f32 v49, s[8:9], v44, v32, v44
	v_fmac_f32_e32 v53, v57, v53
	v_mul_f32_e32 v56, v47, v52
	v_fma_f32 v59, -v40, v55, v41
	v_fmac_f32_e32 v54, v58, v50
	v_mul_f32_e32 v57, v49, v53
	v_fma_f32 v60, -v46, v56, v47
	v_fmac_f32_e32 v55, v59, v51
	v_fma_f32 v34, -v34, v54, v35
	v_fma_f32 v61, -v48, v57, v49
	v_fmac_f32_e32 v56, v60, v52
	v_fma_f32 v35, -v40, v55, v41
	v_div_fmas_f32 v34, v34, v50, v54
	s_mov_b64 vcc, s[4:5]
	v_fmac_f32_e32 v57, v61, v53
	v_fma_f32 v40, -v46, v56, v47
	v_div_fixup_f32 v15, v34, v15, v43
	v_div_fmas_f32 v34, v35, v51, v55
	s_mov_b64 vcc, s[6:7]
	v_fma_f32 v41, -v48, v57, v49
	v_div_fixup_f32 v14, v34, v14, v42
	v_div_fmas_f32 v34, v40, v52, v56
	s_mov_b64 vcc, s[8:9]
	v_pk_mul_f32 v[14:15], v[28:29], v[14:15]
	v_div_fmas_f32 v28, v41, v53, v57
	v_div_fixup_f32 v29, v34, v33, v45
	v_div_fixup_f32 v28, v28, v32, v44
	v_pk_mul_f32 v[28:29], v[30:31], v[28:29]
	v_cvt_pk_bf16_f32 v14, v14, v15
	v_cvt_pk_bf16_f32 v15, v28, v29
	v_mov_b32_e32 v132, v14
	v_mov_b32_e32 v133, v15
	v_mov_b32_e32 v14, v122
	v_mov_b32_e32 v15, v123
	s_waitcnt vmcnt(0)
; __device__ __forceinline__ unsigned cvtpk(float lo, float hi) { f32x2 v = {lo, hi}; bf16x2_t b = __builtin_convertvector(v, bf16x2_t); return __builtin_bit_cast(unsigned, b); }
; __device__ __forceinline__ float bf2f(unsigned u16) { return __uint_as_float(u16 << 16); }
; __device__ __forceinline__ float silu(float g) { return g / (1.f + __expf(-g)); }
; template <int MODE>
; __device__ __forceinline__ void attn_unit(const UnitP& P, ALAS char* lds, const float* __restrict__ sub_gain, const int wv0, unsigned& hgen, unsigned* qctr, const int xcd) {
;     ...
;                 for (int d0 = 0; d0 < 4; ++d0)
; #pragma unroll
;                     for (int g = 0; g < 4; ++g) {
;                         const u32x2 gg = *(const u32x2*)(gp + 32 * d0 + 8 * g);
;                         const f32x4 sg = *(const f32x4*)(sub_gain + 32 * d0 + 8 * g + 4 * hi);
;                         const float y0 = o[d0][4 * g + 0] * rn * sg[0] * silu(bf2f(gg.x & 0xffffu)), y1 = o[d0][4 * g + 1] * rn * sg[1] * silu(bf2f(gg.x >> 16));
;                         const float y2 = o[d0][4 * g + 2] * rn * sg[2] * silu(bf2f(gg.y & 0xffffu)), y3 = o[d0][4 * g + 3] * rn * sg[3] * silu(bf2f(gg.y >> 16));
;                         u32x2 w; w.x = cvtpk(y0, y1); w.y = cvtpk(y2, y3);
;                         *(u32x2*)(mp + 32 * d0 + 8 * g) = w;
	v_pk_mul_f32 v[26:27], v[26:27], v[36:37]
	v_pk_mul_f32 v[24:25], v[24:25], v[38:39]
	v_lshlrev_b32_e32 v30, 16, v14
	v_and_b32_e32 v31, 0xffff0000, v14
	v_lshlrev_b32_e32 v32, 16, v15
	v_and_b32_e32 v33, 0xffff0000, v15
	v_mul_f32_e32 v14, 0xbfb8aa3b, v30
	v_mul_f32_e32 v15, 0xbfb8aa3b, v31
	v_exp_f32_e32 v14, v14
	v_exp_f32_e32 v15, v15
	v_mul_f32_e32 v28, 0xbfb8aa3b, v32
	v_mul_f32_e32 v29, 0xbfb8aa3b, v33
	v_exp_f32_e32 v28, v28
	v_exp_f32_e32 v29, v29
	v_pk_add_f32 v[14:15], v[14:15], 1.0 op_sel_hi:[1,0]
	v_pk_add_f32 v[28:29], v[28:29], 1.0 op_sel_hi:[1,0]
	v_div_scale_f32 v34, s[4:5], v15, v15, v31
	v_div_scale_f32 v36, s[4:5], v14, v14, v30
	v_rcp_f32_e32 v42, v34
	v_div_scale_f32 v38, s[6:7], v29, v29, v33
	v_rcp_f32_e32 v43, v36
	v_div_scale_f32 v40, s[8:9], v28, v28, v32
	v_rcp_f32_e32 v44, v38
	v_rcp_f32_e32 v45, v40
	v_fma_f32 v46, -v34, v42, 1.0
	v_div_scale_f32 v35, vcc, v31, v15, v31
	v_fma_f32 v47, -v36, v43, 1.0
	v_fmac_f32_e32 v42, v46, v42
	v_div_scale_f32 v37, s[4:5], v30, v14, v30
	v_fma_f32 v48, -v38, v44, 1.0
	v_fmac_f32_e32 v43, v47, v43
	v_mul_f32_e32 v46, v35, v42
	v_div_scale_f32 v39, s[6:7], v33, v29, v33
	v_fma_f32 v49, -v40, v45, 1.0
	v_fmac_f32_e32 v44, v48, v44
	v_mul_f32_e32 v47, v37, v43
	v_fma_f32 v50, -v34, v46, v35
	v_div_scale_f32 v41, s[8:9], v32, v28, v32
	v_fmac_f32_e32 v45, v49, v45
	v_mul_f32_e32 v48, v39, v44
	v_fma_f32 v51, -v36, v47, v37
	v_fmac_f32_e32 v46, v50, v42
	v_mul_f32_e32 v49, v41, v45
	v_fma_f32 v52, -v38, v48, v39
	v_fmac_f32_e32 v47, v51, v43
	v_fma_f32 v34, -v34, v46, v35
	v_fma_f32 v53, -v40, v49, v41
	v_fmac_f32_e32 v48, v52, v44
	v_fma_f32 v35, -v36, v47, v37
	v_div_fmas_f32 v34, v34, v42, v46
	s_mov_b64 vcc, s[4:5]
	v_fmac_f32_e32 v49, v53, v45
	v_fma_f32 v36, -v38, v48, v39
	v_div_fixup_f32 v15, v34, v15, v31
	v_div_fmas_f32 v31, v35, v43, v47
	s_mov_b64 vcc, s[6:7]
	v_fma_f32 v37, -v40, v49, v41
	v_div_fixup_f32 v14, v31, v14, v30
	v_div_fmas_f32 v30, v36, v44, v48
	s_mov_b64 vcc, s[8:9]
	v_pk_mul_f32 v[14:15], v[26:27], v[14:15]
	v_div_fmas_f32 v26, v37, v45, v49
	v_div_fixup_f32 v27, v30, v29, v33
	v_div_fixup_f32 v26, v26, v28, v32
	v_pk_mul_f32 v[24:25], v[24:25], v[26:27]
	v_cvt_pk_bf16_f32 v14, v14, v15
	v_cvt_pk_bf16_f32 v15, v24, v25
	v_mov_b32_e32 v134, v14
	v_mov_b32_e32 v135, v15
	s_nop 1
	v_permlane32_swap_b32_e32 v132, v134
	v_permlane32_swap_b32_e32 v133, v135
	global_store_dwordx4 v[136:137], v[132:135], off offset:160
	v_mov_b32_e32 v14, v124
	v_mov_b32_e32 v15, v125
	s_nop 0
	global_load_dwordx4 v[24:27], v13, s[12:13] offset:384
	global_load_dwordx4 v[28:31], v13, s[12:13] offset:416
	v_lshlrev_b32_e32 v34, 16, v14
	v_and_b32_e32 v35, 0xffff0000, v14
	v_lshlrev_b32_e32 v36, 16, v15
	v_and_b32_e32 v37, 0xffff0000, v15
	v_mul_f32_e32 v14, 0xbfb8aa3b, v34
	v_mul_f32_e32 v15, 0xbfb8aa3b, v35
	v_exp_f32_e32 v14, v14
	v_exp_f32_e32 v15, v15
	v_mul_f32_e32 v32, 0xbfb8aa3b, v36
	v_mul_f32_e32 v33, 0xbfb8aa3b, v37
	v_exp_f32_e32 v32, v32
	v_exp_f32_e32 v33, v33
	v_pk_add_f32 v[14:15], v[14:15], 1.0 op_sel_hi:[1,0]
	s_waitcnt vmcnt(0)
	v_pk_mul_f32 v[22:23], v[22:23], v[26:27]
	v_div_scale_f32 v26, s[4:5], v15, v15, v35
	v_pk_mul_f32 v[20:21], v[20:21], v[24:25]
	v_pk_add_f32 v[24:25], v[32:33], 1.0 op_sel_hi:[1,0]
	v_div_scale_f32 v32, s[4:5], v14, v14, v34
	v_rcp_f32_e32 v42, v26
	v_div_scale_f32 v38, s[6:7], v25, v25, v37
	v_rcp_f32_e32 v43, v32
	v_div_scale_f32 v40, s[8:9], v24, v24, v36
	v_rcp_f32_e32 v44, v38
	v_rcp_f32_e32 v45, v40
	v_fma_f32 v46, -v26, v42, 1.0
	v_div_scale_f32 v27, vcc, v35, v15, v35
	v_fma_f32 v47, -v32, v43, 1.0
	v_fmac_f32_e32 v42, v46, v42
	v_div_scale_f32 v33, s[4:5], v34, v14, v34
	v_fma_f32 v48, -v38, v44, 1.0
	v_fmac_f32_e32 v43, v47, v43
	v_mul_f32_e32 v46, v27, v42
	v_div_scale_f32 v39, s[6:7], v37, v25, v37
	v_fma_f32 v49, -v40, v45, 1.0
	v_fmac_f32_e32 v44, v48, v44
	v_mul_f32_e32 v47, v33, v43
	v_fma_f32 v50, -v26, v46, v27
	v_div_scale_f32 v41, s[8:9], v36, v24, v36
	v_fmac_f32_e32 v45, v49, v45
	v_mul_f32_e32 v48, v39, v44
	v_fma_f32 v51, -v32, v47, v33
	v_fmac_f32_e32 v46, v50, v42
	v_mul_f32_e32 v49, v41, v45
	v_fma_f32 v52, -v38, v48, v39
	v_fmac_f32_e32 v47, v51, v43
	v_fma_f32 v26, -v26, v46, v27
	v_fma_f32 v53, -v40, v49, v41
	v_fmac_f32_e32 v48, v52, v44
	v_fma_f32 v27, -v32, v47, v33
	v_div_fmas_f32 v26, v26, v42, v46
	s_mov_b64 vcc, s[4:5]
	v_fmac_f32_e32 v49, v53, v45
	v_fma_f32 v32, -v38, v48, v39
	v_div_fixup_f32 v15, v26, v15, v35
	v_div_fmas_f32 v26, v27, v43, v47
	s_mov_b64 vcc, s[6:7]
	v_fma_f32 v33, -v40, v49, v41
	v_div_fixup_f32 v14, v26, v14, v34
	v_div_fmas_f32 v26, v32, v44, v48
	s_mov_b64 vcc, s[8:9]
	v_pk_mul_f32 v[14:15], v[20:21], v[14:15]
	v_div_fmas_f32 v20, v33, v45, v49
	v_div_fixup_f32 v21, v26, v25, v37
	v_div_fixup_f32 v20, v20, v24, v36
	v_pk_mul_f32 v[20:21], v[22:23], v[20:21]
	v_cvt_pk_bf16_f32 v14, v14, v15
	v_cvt_pk_bf16_f32 v15, v20, v21
	v_mov_b32_e32 v132, v14
	v_mov_b32_e32 v133, v15
	v_mov_b32_e32 v14, v126
	v_mov_b32_e32 v15, v127
	s_waitcnt vmcnt(0)
; __device__ __forceinline__ unsigned cvtpk(float lo, float hi) { f32x2 v = {lo, hi}; bf16x2_t b = __builtin_convertvector(v, bf16x2_t); return __builtin_bit_cast(unsigned, b); }
; __device__ __forceinline__ float bf2f(unsigned u16) { return __uint_as_float(u16 << 16); }
; __device__ __forceinline__ float silu(float g) { return g / (1.f + __expf(-g)); }
; template <int MODE>
; __device__ __forceinline__ void attn_unit(const UnitP& P, ALAS char* lds, const float* __restrict__ sub_gain, const int wv0, unsigned& hgen, unsigned* qctr, const int xcd) {
;     ...
;                 for (int d0 = 0; d0 < 4; ++d0)
; #pragma unroll
;                     for (int g = 0; g < 4; ++g) {
;                         const u32x2 gg = *(const u32x2*)(gp + 32 * d0 + 8 * g);
;                         const f32x4 sg = *(const f32x4*)(sub_gain + 32 * d0 + 8 * g + 4 * hi);
;                         const float y0 = o[d0][4 * g + 0] * rn * sg[0] * silu(bf2f(gg.x & 0xffffu)), y1 = o[d0][4 * g + 1] * rn * sg[1] * silu(bf2f(gg.x >> 16));
;                         const float y2 = o[d0][4 * g + 2] * rn * sg[2] * silu(bf2f(gg.y & 0xffffu)), y3 = o[d0][4 * g + 3] * rn * sg[3] * silu(bf2f(gg.y >> 16));
;                         u32x2 w; w.x = cvtpk(y0, y1); w.y = cvtpk(y2, y3);
;                         *(u32x2*)(mp + 32 * d0 + 8 * g) = w;
	v_pk_mul_f32 v[18:19], v[18:19], v[28:29]
	v_pk_mul_f32 v[16:17], v[16:17], v[30:31]
	v_lshlrev_b32_e32 v22, 16, v14
	v_and_b32_e32 v23, 0xffff0000, v14
	v_lshlrev_b32_e32 v24, 16, v15
	v_and_b32_e32 v25, 0xffff0000, v15
	v_mul_f32_e32 v14, 0xbfb8aa3b, v22
	v_mul_f32_e32 v15, 0xbfb8aa3b, v23
	v_exp_f32_e32 v14, v14
	v_exp_f32_e32 v15, v15
	v_mul_f32_e32 v20, 0xbfb8aa3b, v24
	v_mul_f32_e32 v21, 0xbfb8aa3b, v25
	v_exp_f32_e32 v20, v20
	v_exp_f32_e32 v21, v21
	v_pk_add_f32 v[14:15], v[14:15], 1.0 op_sel_hi:[1,0]
	v_pk_add_f32 v[20:21], v[20:21], 1.0 op_sel_hi:[1,0]
	v_div_scale_f32 v26, s[4:5], v15, v15, v23
	v_div_scale_f32 v28, s[4:5], v14, v14, v22
	v_rcp_f32_e32 v34, v26
	v_div_scale_f32 v30, s[6:7], v21, v21, v25
	v_rcp_f32_e32 v35, v28
	v_div_scale_f32 v32, s[8:9], v20, v20, v24
	v_rcp_f32_e32 v36, v30
	v_rcp_f32_e32 v37, v32
	v_fma_f32 v38, -v26, v34, 1.0
	v_div_scale_f32 v27, vcc, v23, v15, v23
	v_fma_f32 v39, -v28, v35, 1.0
	v_fmac_f32_e32 v34, v38, v34
	v_div_scale_f32 v29, s[4:5], v22, v14, v22
	v_fma_f32 v40, -v30, v36, 1.0
	v_fmac_f32_e32 v35, v39, v35
	v_mul_f32_e32 v38, v27, v34
	v_div_scale_f32 v31, s[6:7], v25, v21, v25
	v_fma_f32 v41, -v32, v37, 1.0
	v_fmac_f32_e32 v36, v40, v36
	v_mul_f32_e32 v39, v29, v35
	v_fma_f32 v42, -v26, v38, v27
	v_div_scale_f32 v33, s[8:9], v24, v20, v24
	v_fmac_f32_e32 v37, v41, v37
	v_mul_f32_e32 v40, v31, v36
	v_fma_f32 v43, -v28, v39, v29
	v_fmac_f32_e32 v38, v42, v34
	v_mul_f32_e32 v41, v33, v37
	v_fma_f32 v44, -v30, v40, v31
	v_fmac_f32_e32 v39, v43, v35
	v_fma_f32 v26, -v26, v38, v27
	v_fma_f32 v45, -v32, v41, v33
	v_fmac_f32_e32 v40, v44, v36
	v_fma_f32 v27, -v28, v39, v29
	v_div_fmas_f32 v26, v26, v34, v38
	s_mov_b64 vcc, s[4:5]
	v_fmac_f32_e32 v41, v45, v37
	v_fma_f32 v28, -v30, v40, v31
	v_div_fixup_f32 v15, v26, v15, v23
	v_div_fmas_f32 v23, v27, v35, v39
	s_mov_b64 vcc, s[6:7]
	v_fma_f32 v29, -v32, v41, v33
	v_div_fixup_f32 v14, v23, v14, v22
	v_div_fmas_f32 v22, v28, v36, v40
	s_mov_b64 vcc, s[8:9]
	v_pk_mul_f32 v[14:15], v[18:19], v[14:15]
	v_div_fmas_f32 v18, v29, v37, v41
	v_div_fixup_f32 v19, v22, v21, v25
	v_div_fixup_f32 v18, v18, v20, v24
	v_pk_mul_f32 v[16:17], v[16:17], v[18:19]
	v_cvt_pk_bf16_f32 v14, v14, v15
	v_cvt_pk_bf16_f32 v15, v16, v17
	v_mov_b32_e32 v134, v14
	v_mov_b32_e32 v135, v15
	s_nop 1
	v_permlane32_swap_b32_e32 v132, v134
	v_permlane32_swap_b32_e32 v133, v135
	global_store_dwordx4 v[136:137], v[132:135], off offset:192
	v_mov_b32_e32 v22, v128
	v_mov_b32_e32 v23, v129
	s_nop 0
	global_load_dwordx4 v[14:17], v13, s[12:13] offset:448
	global_load_dwordx4 v[18:21], v13, s[12:13] offset:480
	v_lshlrev_b32_e32 v13, 16, v22
	v_and_b32_e32 v26, 0xffff0000, v22
	v_lshlrev_b32_e32 v27, 16, v23
	v_and_b32_e32 v28, 0xffff0000, v23
	v_mul_f32_e32 v22, 0xbfb8aa3b, v13
	v_mul_f32_e32 v23, 0xbfb8aa3b, v26
	v_exp_f32_e32 v22, v22
	v_exp_f32_e32 v23, v23
	v_mul_f32_e32 v24, 0xbfb8aa3b, v27
	v_mul_f32_e32 v25, 0xbfb8aa3b, v28
	v_exp_f32_e32 v24, v24
	v_exp_f32_e32 v25, v25
	s_waitcnt vmcnt(0)
; __device__ __forceinline__ unsigned cvtpk(float lo, float hi) { f32x2 v = {lo, hi}; bf16x2_t b = __builtin_convertvector(v, bf16x2_t); return __builtin_bit_cast(unsigned, b); }
; __device__ __forceinline__ float bf2f(unsigned u16) { return __uint_as_float(u16 << 16); }
; __device__ __forceinline__ float silu(float g) { return g / (1.f + __expf(-g)); }
; template <int MODE>
; __device__ __forceinline__ void attn_unit(const UnitP& P, ALAS char* lds, const float* __restrict__ sub_gain, const int wv0, unsigned& hgen, unsigned* qctr, const int xcd) {
;     ...
;                 for (int d0 = 0; d0 < 4; ++d0)
; #pragma unroll
;                     for (int g = 0; g < 4; ++g) {
;                         const u32x2 gg = *(const u32x2*)(gp + 32 * d0 + 8 * g);
;                         const f32x4 sg = *(const f32x4*)(sub_gain + 32 * d0 + 8 * g + 4 * hi);
;                         const float y0 = o[d0][4 * g + 0] * rn * sg[0] * silu(bf2f(gg.x & 0xffffu)), y1 = o[d0][4 * g + 1] * rn * sg[1] * silu(bf2f(gg.x >> 16));
;                         const float y2 = o[d0][4 * g + 2] * rn * sg[2] * silu(bf2f(gg.y & 0xffffu)), y3 = o[d0][4 * g + 3] * rn * sg[3] * silu(bf2f(gg.y >> 16));
;                         u32x2 w; w.x = cvtpk(y0, y1); w.y = cvtpk(y2, y3);
;                         *(u32x2*)(mp + 32 * d0 + 8 * g) = w;
	v_pk_mul_f32 v[8:9], v[8:9], v[14:15]
	v_pk_add_f32 v[14:15], v[22:23], 1.0 op_sel_hi:[1,0]
	v_pk_mul_f32 v[10:11], v[10:11], v[16:17]
	v_div_scale_f32 v22, s[4:5], v15, v15, v26
	v_pk_add_f32 v[16:17], v[24:25], 1.0 op_sel_hi:[1,0]
	v_div_scale_f32 v24, s[4:5], v14, v14, v13
	v_rcp_f32_e32 v33, v22
	v_div_scale_f32 v29, s[6:7], v17, v17, v28
	v_rcp_f32_e32 v34, v24
	v_div_scale_f32 v31, s[8:9], v16, v16, v27
	v_rcp_f32_e32 v35, v29
	v_rcp_f32_e32 v36, v31
	v_fma_f32 v37, -v22, v33, 1.0
	v_div_scale_f32 v23, vcc, v26, v15, v26
	v_fma_f32 v38, -v24, v34, 1.0
	v_fmac_f32_e32 v33, v37, v33
	v_div_scale_f32 v25, s[4:5], v13, v14, v13
	v_fma_f32 v39, -v29, v35, 1.0
	v_fmac_f32_e32 v34, v38, v34
	v_mul_f32_e32 v37, v23, v33
	v_div_scale_f32 v30, s[6:7], v28, v17, v28
	v_fma_f32 v40, -v31, v36, 1.0
	v_fmac_f32_e32 v35, v39, v35
	v_mul_f32_e32 v38, v25, v34
	v_fma_f32 v41, -v22, v37, v23
	v_div_scale_f32 v32, s[8:9], v27, v16, v27
	v_fmac_f32_e32 v36, v40, v36
	v_mul_f32_e32 v39, v30, v35
	v_fma_f32 v42, -v24, v38, v25
	v_fmac_f32_e32 v37, v41, v33
	v_mul_f32_e32 v40, v32, v36
	v_fma_f32 v43, -v29, v39, v30
	v_fmac_f32_e32 v38, v42, v34
	v_fma_f32 v22, -v22, v37, v23
	v_fma_f32 v44, -v31, v40, v32
	v_fmac_f32_e32 v39, v43, v35
	v_fma_f32 v23, -v24, v38, v25
	v_div_fmas_f32 v22, v22, v33, v37
	s_mov_b64 vcc, s[4:5]
	v_fmac_f32_e32 v40, v44, v36
	v_fma_f32 v24, -v29, v39, v30
	v_div_fixup_f32 v15, v22, v15, v26
	v_div_fmas_f32 v22, v23, v34, v38
	s_mov_b64 vcc, s[6:7]
	v_fma_f32 v25, -v31, v40, v32
	v_div_fixup_f32 v14, v22, v14, v13
	v_div_fmas_f32 v13, v24, v35, v39
	s_mov_b64 vcc, s[8:9]
	v_pk_mul_f32 v[8:9], v[8:9], v[14:15]
	v_div_fixup_f32 v15, v13, v17, v28
	v_div_fmas_f32 v13, v25, v36, v40
	v_div_fixup_f32 v14, v13, v16, v27
	v_pk_mul_f32 v[10:11], v[10:11], v[14:15]
	v_cvt_pk_bf16_f32 v8, v8, v9
	v_cvt_pk_bf16_f32 v9, v10, v11
	v_mov_b32_e32 v132, v8
	v_mov_b32_e32 v133, v9
	v_mov_b32_e32 v6, v130
	v_mov_b32_e32 v7, v131
	v_pk_mul_f32 v[2:3], v[2:3], v[12:13] op_sel_hi:[1,0]
	v_pk_mul_f32 v[0:1], v[0:1], v[12:13] op_sel_hi:[1,0]
	s_waitcnt vmcnt(0)
	v_pk_mul_f32 v[2:3], v[2:3], v[18:19]
	v_pk_mul_f32 v[0:1], v[0:1], v[20:21]
	v_lshlrev_b32_e32 v10, 16, v6
	v_and_b32_e32 v11, 0xffff0000, v6
	v_lshlrev_b32_e32 v12, 16, v7
	v_and_b32_e32 v13, 0xffff0000, v7
	v_mul_f32_e32 v6, 0xbfb8aa3b, v10
	v_mul_f32_e32 v7, 0xbfb8aa3b, v11
	v_exp_f32_e32 v6, v6
	v_exp_f32_e32 v7, v7
	v_mul_f32_e32 v8, 0xbfb8aa3b, v12
	v_mul_f32_e32 v9, 0xbfb8aa3b, v13
	v_exp_f32_e32 v8, v8
	v_exp_f32_e32 v9, v9
	v_pk_add_f32 v[6:7], v[6:7], 1.0 op_sel_hi:[1,0]
	v_pk_add_f32 v[8:9], v[8:9], 1.0 op_sel_hi:[1,0]
	v_div_scale_f32 v14, s[4:5], v7, v7, v11
	v_div_scale_f32 v16, s[4:5], v6, v6, v10
	v_rcp_f32_e32 v22, v14
	v_div_scale_f32 v18, s[6:7], v9, v9, v13
	v_rcp_f32_e32 v23, v16
	v_div_scale_f32 v20, s[8:9], v8, v8, v12
	v_rcp_f32_e32 v24, v18
	v_rcp_f32_e32 v25, v20
	v_fma_f32 v26, -v14, v22, 1.0
	v_div_scale_f32 v15, vcc, v11, v7, v11
	v_fma_f32 v27, -v16, v23, 1.0
	v_fmac_f32_e32 v22, v26, v22
	v_div_scale_f32 v17, s[4:5], v10, v6, v10
	v_fma_f32 v28, -v18, v24, 1.0
	v_fmac_f32_e32 v23, v27, v23
	v_mul_f32_e32 v26, v15, v22
	v_div_scale_f32 v19, s[6:7], v13, v9, v13
	v_fma_f32 v29, -v20, v25, 1.0
	v_fmac_f32_e32 v24, v28, v24
	v_mul_f32_e32 v27, v17, v23
	v_fma_f32 v30, -v14, v26, v15
	v_div_scale_f32 v21, s[8:9], v12, v8, v12
	v_fmac_f32_e32 v25, v29, v25
	v_mul_f32_e32 v28, v19, v24
	v_fma_f32 v31, -v16, v27, v17
	v_fmac_f32_e32 v26, v30, v22
	v_mul_f32_e32 v29, v21, v25
	v_fma_f32 v32, -v18, v28, v19
	v_fmac_f32_e32 v27, v31, v23
	v_fma_f32 v14, -v14, v26, v15
	v_fma_f32 v33, -v20, v29, v21
	v_fmac_f32_e32 v28, v32, v24
	v_fma_f32 v15, -v16, v27, v17
	v_div_fmas_f32 v14, v14, v22, v26
	s_mov_b64 vcc, s[4:5]
	v_fmac_f32_e32 v29, v33, v25
	v_fma_f32 v16, -v18, v28, v19
	v_div_fixup_f32 v7, v14, v7, v11
	v_div_fmas_f32 v11, v15, v23, v27
	s_mov_b64 vcc, s[6:7]
	v_fma_f32 v17, -v20, v29, v21
	v_div_fixup_f32 v6, v11, v6, v10
	v_div_fmas_f32 v10, v16, v24, v28
	s_mov_b64 vcc, s[8:9]
	v_pk_mul_f32 v[2:3], v[2:3], v[6:7]
	v_div_fmas_f32 v6, v17, v25, v29
	v_div_fixup_f32 v7, v10, v9, v13
	v_div_fixup_f32 v6, v6, v8, v12
	v_pk_mul_f32 v[0:1], v[0:1], v[6:7]
	v_cvt_pk_bf16_f32 v2, v2, v3
	v_cvt_pk_bf16_f32 v3, v0, v1
	v_mov_b32_e32 v134, v2
	v_mov_b32_e32 v135, v3
	s_nop 1
	v_permlane32_swap_b32_e32 v132, v134
	v_permlane32_swap_b32_e32 v133, v135
	global_store_dwordx4 v[136:137], v[132:135], off offset:224

; __device__ __forceinline__ float sum32(float v) { auto rr = __builtin_amdgcn_permlane32_swap(__float_as_uint(v), __float_as_uint(v), false, false); return __uint_as_float(rr[0]) + __uint_as_float(rr[1]); }
; __device__ __forceinline__ unsigned cvtpk(float lo, float hi) { f32x2 v = {lo, hi}; bf16x2_t b = __builtin_convertvector(v, bf16x2_t); return __builtin_bit_cast(unsigned, b); }
; __device__ __forceinline__ float bf2f(unsigned u16) { return __uint_as_float(u16 << 16); }
; __device__ __forceinline__ float silu(float g) { return g / (1.f + __expf(-g)); }
; template <int MODE>
; __device__ __forceinline__ void attn_unit(const UnitP& P, ALAS char* lds, const float* __restrict__ sub_gain, const int wv0, unsigned& hgen, unsigned* qctr, const int xcd) {
;     ...
;     lsum = sum32(lsum);
;     const int qrow = qw0 + r32;
;     if constexpr (MODE == 1) {
;         if (active && qrow < P.nq && P.dry == 0) {
;             const float inv = 1.f / lsum;
;             const bf16_t* gp = P.G + (size_t)qrow * 8192 + 4 * hi;
;             bf16_t* mp = P.Mo + (size_t)qrow * 2048 + 4 * hi;
; #pragma unroll
;             for (int d0 = 0; d0 < 4; ++d0)
; #pragma unroll
;                 for (int g = 0; g < 4; ++g) {
;                     const u32x2 gg = *(const u32x2*)(gp + 32 * d0 + 8 * g);
;                     const float y0 = o[d0][4 * g + 0] * inv * silu(bf2f(gg.x & 0xffffu)), y1 = o[d0][4 * g + 1] * inv * silu(bf2f(gg.x >> 16));
;                     const float y2 = o[d0][4 * g + 2] * inv * silu(bf2f(gg.y & 0xffffu)), y3 = o[d0][4 * g + 3] * inv * silu(bf2f(gg.y >> 16));
;                     u32x2 w; w.x = cvtpk(y0, y1); w.y = cvtpk(y2, y3);
;                     *(u32x2*)(mp + 32 * d0 + 8 * g) = w;
.LBB0_417:
	v_readlane_b32 s0, v252, 44
	v_mov_b32_e32 v64, v204
	s_nop 1
	v_permlane32_swap_b32_e32 v204, v64
	v_cmp_gt_u32_e32 vcc, s0, v200
	s_and_b64 s[4:5], s[74:75], vcc
	s_and_saveexec_b64 s[0:1], s[4:5]
	s_cbranch_execz .LBB0_218
	v_readlane_b32 s4, v252, 40
	v_mov_b32_e32 v179, v177
	v_readlane_b32 s5, v252, 41
	v_lshlrev_b32_e32 v176, 1, v181
	v_mov_b32_e32 v65, v177
	v_lshl_add_u64 v[66:67], s[4:5], 0, v[178:179]
	v_lshl_add_u64 v[68:69], v[66:67], 0, v[176:177]
	global_load_dwordx2 v[70:71], v[68:69], off
	global_load_dwordx2 v[98:99], v[68:69], off offset:16
	global_load_dwordx2 v[100:101], v[68:69], off offset:32
	global_load_dwordx2 v[102:103], v[68:69], off offset:48
	global_load_dwordx2 v[104:105], v[68:69], off offset:64
	global_load_dwordx2 v[106:107], v[68:69], off offset:80
	global_load_dwordx2 v[108:109], v[68:69], off offset:96
	global_load_dwordx2 v[110:111], v[68:69], off offset:112
	global_load_dwordx2 v[112:113], v[68:69], off offset:128
	global_load_dwordx2 v[114:115], v[68:69], off offset:144
	global_load_dwordx2 v[116:117], v[68:69], off offset:160
	global_load_dwordx2 v[118:119], v[68:69], off offset:176
	global_load_dwordx2 v[120:121], v[68:69], off offset:192
	global_load_dwordx2 v[122:123], v[68:69], off offset:208
	global_load_dwordx2 v[124:125], v[68:69], off offset:224
	global_load_dwordx2 v[126:127], v[68:69], off offset:240
	v_add_f32_e32 v66, v204, v64
	v_div_scale_f32 v67, s[4:5], v66, v66, 1.0
	v_rcp_f32_e32 v72, v67
	v_div_scale_f32 v73, vcc, 1.0, v66, 1.0
	v_readlane_b32 s4, v252, 42
	v_fma_f32 v74, -v67, v72, 1.0
	v_fmac_f32_e32 v72, v74, v72
	v_mul_f32_e32 v74, v73, v72
	v_fma_f32 v75, -v67, v74, v73
	v_fmac_f32_e32 v74, v75, v72
	v_fma_f32 v67, -v67, v74, v73
	v_div_fmas_f32 v67, v67, v72, v74
	v_div_fixup_f32 v66, v67, v66, 1.0
	v_lshlrev_b32_e32 v64, 12, v200
	v_readlane_b32 s5, v252, 43
	s_waitcnt vmcnt(0)
	v_lshlrev_b32_e32 v67, 16, v70
	v_and_b32_e32 v74, 0xffff0000, v70
	v_lshlrev_b32_e32 v75, 16, v71
	v_and_b32_e32 v76, 0xffff0000, v71
	v_mul_f32_e32 v70, 0xbfb8aa3b, v67
	v_mul_f32_e32 v71, 0xbfb8aa3b, v74
	v_exp_f32_e32 v70, v70
	v_exp_f32_e32 v71, v71
	v_mul_f32_e32 v72, 0xbfb8aa3b, v75
	v_mul_f32_e32 v73, 0xbfb8aa3b, v76
	v_exp_f32_e32 v72, v72
	v_exp_f32_e32 v73, v73
	v_pk_add_f32 v[70:71], v[70:71], 1.0 op_sel_hi:[1,0]
	v_lshl_add_u64 v[64:65], s[4:5], 0, v[64:65]
	v_div_scale_f32 v77, s[4:5], v71, v71, v74
	v_pk_add_f32 v[72:73], v[72:73], 1.0 op_sel_hi:[1,0]
	v_div_scale_f32 v79, s[4:5], v70, v70, v67
	v_rcp_f32_e32 v85, v77
	v_div_scale_f32 v81, s[6:7], v73, v73, v76
	v_rcp_f32_e32 v86, v79
	v_div_scale_f32 v83, s[8:9], v72, v72, v75
	v_rcp_f32_e32 v87, v81
	v_rcp_f32_e32 v88, v83
	v_fma_f32 v89, -v77, v85, 1.0
	v_div_scale_f32 v78, vcc, v74, v71, v74
	v_fma_f32 v90, -v79, v86, 1.0
	v_fmac_f32_e32 v85, v89, v85
	v_div_scale_f32 v80, s[4:5], v67, v70, v67
	v_fma_f32 v91, -v81, v87, 1.0
	v_fmac_f32_e32 v86, v90, v86
	v_mul_f32_e32 v89, v78, v85
	v_div_scale_f32 v82, s[6:7], v76, v73, v76
	v_fma_f32 v92, -v83, v88, 1.0
	v_fmac_f32_e32 v87, v91, v87
	v_mul_f32_e32 v90, v80, v86
	v_fma_f32 v93, -v77, v89, v78
	v_div_scale_f32 v84, s[8:9], v75, v72, v75
	v_fmac_f32_e32 v88, v92, v88
	v_mul_f32_e32 v91, v82, v87
	v_fma_f32 v94, -v79, v90, v80
	v_fmac_f32_e32 v89, v93, v85
	v_mul_f32_e32 v92, v84, v88
	v_fma_f32 v95, -v81, v91, v82
	v_fmac_f32_e32 v90, v94, v86
	v_fma_f32 v77, -v77, v89, v78
	v_fma_f32 v96, -v83, v92, v84
	v_fmac_f32_e32 v91, v95, v87
	v_fma_f32 v78, -v79, v90, v80
	v_div_fmas_f32 v77, v77, v85, v89
	s_mov_b64 vcc, s[4:5]
	v_fmac_f32_e32 v92, v96, v88
	v_fma_f32 v79, -v81, v91, v82
	v_div_fixup_f32 v71, v77, v71, v74
	v_div_fmas_f32 v74, v78, v86, v90
	s_mov_b64 vcc, s[6:7]
	v_pk_mul_f32 v[48:49], v[48:49], v[66:67] op_sel_hi:[1,0]
	v_pk_mul_f32 v[50:51], v[50:51], v[66:67] op_sel_hi:[1,0]
	v_fma_f32 v80, -v83, v92, v84
	v_div_fixup_f32 v70, v74, v70, v67
	v_div_fmas_f32 v67, v79, v87, v91
	s_mov_b64 vcc, s[8:9]
	v_pk_mul_f32 v[48:49], v[48:49], v[70:71]
	v_div_fixup_f32 v71, v67, v73, v76
	v_div_fmas_f32 v67, v80, v88, v92
	v_div_fixup_f32 v70, v67, v72, v75
	v_pk_mul_f32 v[50:51], v[50:51], v[70:71]
	v_lshl_add_u64 v[64:65], v[64:65], 0, v[176:177]
	v_cvt_pk_bf16_f32 v48, v48, v49
	v_cvt_pk_bf16_f32 v49, v50, v51
	v_mov_b32_e32 v128, v48
	v_mov_b32_e32 v129, v49
	v_mov_b32_e32 v48, v98
	v_mov_b32_e32 v49, v99
	v_lshlrev_b32_e32 v67, 16, v48
	v_and_b32_e32 v70, 0xffff0000, v48
	v_lshlrev_b32_e32 v71, 16, v49
	v_and_b32_e32 v72, 0xffff0000, v49
	v_mul_f32_e32 v48, 0xbfb8aa3b, v67
	v_mul_f32_e32 v49, 0xbfb8aa3b, v70
	v_exp_f32_e32 v48, v48
	v_exp_f32_e32 v49, v49
	v_mul_f32_e32 v50, 0xbfb8aa3b, v71
	v_mul_f32_e32 v51, 0xbfb8aa3b, v72
	v_exp_f32_e32 v50, v50
	v_exp_f32_e32 v51, v51
	v_pk_add_f32 v[48:49], v[48:49], 1.0 op_sel_hi:[1,0]
	v_pk_mul_f32 v[52:53], v[52:53], v[66:67] op_sel_hi:[1,0]
	v_div_scale_f32 v73, s[4:5], v49, v49, v70
	v_pk_add_f32 v[50:51], v[50:51], 1.0 op_sel_hi:[1,0]
	v_div_scale_f32 v75, s[4:5], v48, v48, v67
	v_rcp_f32_e32 v81, v73
	v_div_scale_f32 v77, s[6:7], v51, v51, v72
	v_rcp_f32_e32 v82, v75
	v_div_scale_f32 v79, s[8:9], v50, v50, v71
	v_rcp_f32_e32 v83, v77
	v_rcp_f32_e32 v84, v79
	v_fma_f32 v85, -v73, v81, 1.0
	v_div_scale_f32 v74, vcc, v70, v49, v70
	v_fma_f32 v86, -v75, v82, 1.0
	v_fmac_f32_e32 v81, v85, v81
	v_div_scale_f32 v76, s[4:5], v67, v48, v67
	v_fma_f32 v87, -v77, v83, 1.0
	v_fmac_f32_e32 v82, v86, v82
	v_mul_f32_e32 v85, v74, v81
	v_div_scale_f32 v78, s[6:7], v72, v51, v72
	v_fma_f32 v88, -v79, v84, 1.0
	v_fmac_f32_e32 v83, v87, v83
	v_mul_f32_e32 v86, v76, v82
	v_fma_f32 v89, -v73, v85, v74
	v_div_scale_f32 v80, s[8:9], v71, v50, v71
; __device__ __forceinline__ unsigned cvtpk(float lo, float hi) { f32x2 v = {lo, hi}; bf16x2_t b = __builtin_convertvector(v, bf16x2_t); return __builtin_bit_cast(unsigned, b); }
; __device__ __forceinline__ float bf2f(unsigned u16) { return __uint_as_float(u16 << 16); }
; __device__ __forceinline__ float silu(float g) { return g / (1.f + __expf(-g)); }
; template <int MODE>
; __device__ __forceinline__ void attn_unit(const UnitP& P, ALAS char* lds, const float* __restrict__ sub_gain, const int wv0, unsigned& hgen, unsigned* qctr, const int xcd) {
;     ...
; #pragma unroll
;             for (int d0 = 0; d0 < 4; ++d0)
; #pragma unroll
;                 for (int g = 0; g < 4; ++g) {
;                     const u32x2 gg = *(const u32x2*)(gp + 32 * d0 + 8 * g);
;                     const float y0 = o[d0][4 * g + 0] * inv * silu(bf2f(gg.x & 0xffffu)), y1 = o[d0][4 * g + 1] * inv * silu(bf2f(gg.x >> 16));
;                     const float y2 = o[d0][4 * g + 2] * inv * silu(bf2f(gg.y & 0xffffu)), y3 = o[d0][4 * g + 3] * inv * silu(bf2f(gg.y >> 16));
;                     u32x2 w; w.x = cvtpk(y0, y1); w.y = cvtpk(y2, y3);
;                     *(u32x2*)(mp + 32 * d0 + 8 * g) = w;
	v_fmac_f32_e32 v84, v88, v84
	v_mul_f32_e32 v87, v78, v83
	v_fma_f32 v90, -v75, v86, v76
	v_fmac_f32_e32 v85, v89, v81
	v_mul_f32_e32 v88, v80, v84
	v_fma_f32 v91, -v77, v87, v78
	v_fmac_f32_e32 v86, v90, v82
	v_fma_f32 v73, -v73, v85, v74
	v_fma_f32 v92, -v79, v88, v80
	v_fmac_f32_e32 v87, v91, v83
	v_fma_f32 v74, -v75, v86, v76
	v_div_fmas_f32 v73, v73, v81, v85
	s_mov_b64 vcc, s[4:5]
	v_fmac_f32_e32 v88, v92, v84
	v_fma_f32 v75, -v77, v87, v78
	v_div_fixup_f32 v49, v73, v49, v70
	v_div_fmas_f32 v70, v74, v82, v86
	s_mov_b64 vcc, s[6:7]
	v_pk_mul_f32 v[54:55], v[54:55], v[66:67] op_sel_hi:[1,0]
	v_fma_f32 v76, -v79, v88, v80
	v_div_fixup_f32 v48, v70, v48, v67
	v_div_fmas_f32 v67, v75, v83, v87
	s_mov_b64 vcc, s[8:9]
	v_pk_mul_f32 v[48:49], v[52:53], v[48:49]
	v_div_fmas_f32 v52, v76, v84, v88
	v_div_fixup_f32 v51, v67, v51, v72
	v_div_fixup_f32 v50, v52, v50, v71
	v_pk_mul_f32 v[50:51], v[54:55], v[50:51]
	v_cvt_pk_bf16_f32 v48, v48, v49
	v_cvt_pk_bf16_f32 v49, v50, v51
	v_mov_b32_e32 v130, v48
	v_mov_b32_e32 v131, v49
	v_mbcnt_lo_u32_b32 v134, -1, 0
	v_mbcnt_hi_u32_b32 v134, -1, v134
	v_and_b32_e32 v134, 32, v134
	v_lshrrev_b32_e32 v134, 2, v134
	v_mov_b32_e32 v135, 0
	v_lshl_add_u64 v[132:133], v[64:65], 0, v[134:135]
	v_permlane32_swap_b32_e32 v128, v130
	v_permlane32_swap_b32_e32 v129, v131
	global_store_dwordx4 v[132:133], v[128:131], off
	v_mov_b32_e32 v48, v100
	v_mov_b32_e32 v49, v101
	v_lshlrev_b32_e32 v67, 16, v48
	v_and_b32_e32 v70, 0xffff0000, v48
	v_lshlrev_b32_e32 v71, 16, v49
	v_and_b32_e32 v72, 0xffff0000, v49
	v_mul_f32_e32 v48, 0xbfb8aa3b, v67
	v_mul_f32_e32 v49, 0xbfb8aa3b, v70
	v_exp_f32_e32 v48, v48
	v_exp_f32_e32 v49, v49
	v_mul_f32_e32 v50, 0xbfb8aa3b, v71
	v_mul_f32_e32 v51, 0xbfb8aa3b, v72
	v_exp_f32_e32 v50, v50
	v_exp_f32_e32 v51, v51
	v_pk_add_f32 v[48:49], v[48:49], 1.0 op_sel_hi:[1,0]
	v_pk_mul_f32 v[52:53], v[56:57], v[66:67] op_sel_hi:[1,0]
	v_div_scale_f32 v56, s[4:5], v49, v49, v70
	v_pk_mul_f32 v[54:55], v[58:59], v[66:67] op_sel_hi:[1,0]
	v_pk_add_f32 v[50:51], v[50:51], 1.0 op_sel_hi:[1,0]
	v_div_scale_f32 v58, s[4:5], v48, v48, v67
	v_rcp_f32_e32 v77, v56
	v_div_scale_f32 v73, s[6:7], v51, v51, v72
	v_rcp_f32_e32 v78, v58
	v_div_scale_f32 v75, s[8:9], v50, v50, v71
	v_rcp_f32_e32 v79, v73
	v_rcp_f32_e32 v80, v75
	v_fma_f32 v81, -v56, v77, 1.0
	v_div_scale_f32 v57, vcc, v70, v49, v70
	v_fma_f32 v82, -v58, v78, 1.0
	v_fmac_f32_e32 v77, v81, v77
	v_div_scale_f32 v59, s[4:5], v67, v48, v67
	v_fma_f32 v83, -v73, v79, 1.0
	v_fmac_f32_e32 v78, v82, v78
	v_mul_f32_e32 v81, v57, v77
	v_div_scale_f32 v74, s[6:7], v72, v51, v72
	v_fma_f32 v84, -v75, v80, 1.0
	v_fmac_f32_e32 v79, v83, v79
	v_mul_f32_e32 v82, v59, v78
	v_fma_f32 v85, -v56, v81, v57
	v_div_scale_f32 v76, s[8:9], v71, v50, v71
	v_fmac_f32_e32 v80, v84, v80
	v_mul_f32_e32 v83, v74, v79
	v_fma_f32 v86, -v58, v82, v59
	v_fmac_f32_e32 v81, v85, v77
	v_mul_f32_e32 v84, v76, v80
	v_fma_f32 v87, -v73, v83, v74
	v_fmac_f32_e32 v82, v86, v78
	v_fma_f32 v56, -v56, v81, v57
	v_fma_f32 v88, -v75, v84, v76
	v_fmac_f32_e32 v83, v87, v79
	v_fma_f32 v57, -v58, v82, v59
	v_div_fmas_f32 v56, v56, v77, v81
	s_mov_b64 vcc, s[4:5]
	v_fmac_f32_e32 v84, v88, v80
	v_fma_f32 v58, -v73, v83, v74
	v_div_fixup_f32 v49, v56, v49, v70
	v_div_fmas_f32 v56, v57, v78, v82
	s_mov_b64 vcc, s[6:7]
	v_fma_f32 v59, -v75, v84, v76
	v_div_fixup_f32 v48, v56, v48, v67
	v_div_fmas_f32 v56, v58, v79, v83
	s_mov_b64 vcc, s[8:9]
	v_pk_mul_f32 v[48:49], v[52:53], v[48:49]
	v_div_fmas_f32 v52, v59, v80, v84
	v_div_fixup_f32 v51, v56, v51, v72
	v_div_fixup_f32 v50, v52, v50, v71
	v_pk_mul_f32 v[50:51], v[54:55], v[50:51]
	v_cvt_pk_bf16_f32 v48, v48, v49
	v_cvt_pk_bf16_f32 v49, v50, v51
	v_mov_b32_e32 v128, v48
	v_mov_b32_e32 v129, v49
	v_mov_b32_e32 v48, v102
	v_mov_b32_e32 v49, v103
	v_pk_mul_f32 v[52:53], v[60:61], v[66:67] op_sel_hi:[1,0]
	v_pk_mul_f32 v[54:55], v[62:63], v[66:67] op_sel_hi:[1,0]
	v_lshlrev_b32_e32 v56, 16, v48
	v_and_b32_e32 v57, 0xffff0000, v48
	v_lshlrev_b32_e32 v58, 16, v49
	v_and_b32_e32 v59, 0xffff0000, v49
	v_mul_f32_e32 v48, 0xbfb8aa3b, v56
	v_mul_f32_e32 v49, 0xbfb8aa3b, v57
	v_exp_f32_e32 v48, v48
	v_exp_f32_e32 v49, v49
	v_mul_f32_e32 v50, 0xbfb8aa3b, v58
	v_mul_f32_e32 v51, 0xbfb8aa3b, v59
	v_exp_f32_e32 v50, v50
	v_exp_f32_e32 v51, v51
	v_pk_add_f32 v[48:49], v[48:49], 1.0 op_sel_hi:[1,0]
	v_pk_add_f32 v[50:51], v[50:51], 1.0 op_sel_hi:[1,0]
	v_div_scale_f32 v60, s[4:5], v49, v49, v57
	v_div_scale_f32 v62, s[4:5], v48, v48, v56
	v_rcp_f32_e32 v73, v60
	v_div_scale_f32 v67, s[6:7], v51, v51, v59
	v_rcp_f32_e32 v74, v62
	v_div_scale_f32 v71, s[8:9], v50, v50, v58
	v_rcp_f32_e32 v75, v67
	v_rcp_f32_e32 v76, v71
	v_fma_f32 v77, -v60, v73, 1.0
	v_div_scale_f32 v61, vcc, v57, v49, v57
	v_fma_f32 v78, -v62, v74, 1.0
	v_fmac_f32_e32 v73, v77, v73
	v_div_scale_f32 v63, s[4:5], v56, v48, v56
	v_fma_f32 v79, -v67, v75, 1.0
	v_fmac_f32_e32 v74, v78, v74
	v_mul_f32_e32 v77, v61, v73
	v_div_scale_f32 v70, s[6:7], v59, v51, v59
	v_fma_f32 v80, -v71, v76, 1.0
	v_fmac_f32_e32 v75, v79, v75
	v_mul_f32_e32 v78, v63, v74
	v_fma_f32 v81, -v60, v77, v61
	v_div_scale_f32 v72, s[8:9], v58, v50, v58
	v_fmac_f32_e32 v76, v80, v76
	v_mul_f32_e32 v79, v70, v75
	v_fma_f32 v82, -v62, v78, v63
	v_fmac_f32_e32 v77, v81, v73
	v_mul_f32_e32 v80, v72, v76
	v_fma_f32 v83, -v67, v79, v70
	v_fmac_f32_e32 v78, v82, v74
	v_fma_f32 v60, -v60, v77, v61
	v_fma_f32 v84, -v71, v80, v72
	v_fmac_f32_e32 v79, v83, v75
	v_fma_f32 v61, -v62, v78, v63
	v_div_fmas_f32 v60, v60, v73, v77
	s_mov_b64 vcc, s[4:5]
	v_fmac_f32_e32 v80, v84, v76
	v_fma_f32 v62, -v67, v79, v70
	v_div_fixup_f32 v49, v60, v49, v57
; __device__ __forceinline__ unsigned cvtpk(float lo, float hi) { f32x2 v = {lo, hi}; bf16x2_t b = __builtin_convertvector(v, bf16x2_t); return __builtin_bit_cast(unsigned, b); }
; __device__ __forceinline__ float bf2f(unsigned u16) { return __uint_as_float(u16 << 16); }
; __device__ __forceinline__ float silu(float g) { return g / (1.f + __expf(-g)); }
; template <int MODE>
; __device__ __forceinline__ void attn_unit(const UnitP& P, ALAS char* lds, const float* __restrict__ sub_gain, const int wv0, unsigned& hgen, unsigned* qctr, const int xcd) {
;     ...
; #pragma unroll
;             for (int d0 = 0; d0 < 4; ++d0)
; #pragma unroll
;                 for (int g = 0; g < 4; ++g) {
;                     const u32x2 gg = *(const u32x2*)(gp + 32 * d0 + 8 * g);
;                     const float y0 = o[d0][4 * g + 0] * inv * silu(bf2f(gg.x & 0xffffu)), y1 = o[d0][4 * g + 1] * inv * silu(bf2f(gg.x >> 16));
;                     const float y2 = o[d0][4 * g + 2] * inv * silu(bf2f(gg.y & 0xffffu)), y3 = o[d0][4 * g + 3] * inv * silu(bf2f(gg.y >> 16));
;                     u32x2 w; w.x = cvtpk(y0, y1); w.y = cvtpk(y2, y3);
;                     *(u32x2*)(mp + 32 * d0 + 8 * g) = w;
	v_div_fmas_f32 v57, v61, v74, v78
	s_mov_b64 vcc, s[6:7]
	v_fma_f32 v63, -v71, v80, v72
	v_div_fixup_f32 v48, v57, v48, v56
	v_div_fmas_f32 v56, v62, v75, v79
	s_mov_b64 vcc, s[8:9]
	v_pk_mul_f32 v[48:49], v[52:53], v[48:49]
	v_div_fmas_f32 v52, v63, v76, v80
	v_div_fixup_f32 v51, v56, v51, v59
	v_div_fixup_f32 v50, v52, v50, v58
	v_pk_mul_f32 v[50:51], v[54:55], v[50:51]
	v_cvt_pk_bf16_f32 v48, v48, v49
	v_cvt_pk_bf16_f32 v49, v50, v51
	v_mov_b32_e32 v130, v48
	v_mov_b32_e32 v131, v49
	s_nop 1
	v_permlane32_swap_b32_e32 v128, v130
	v_permlane32_swap_b32_e32 v129, v131
	global_store_dwordx4 v[132:133], v[128:131], off offset:32
	v_mov_b32_e32 v48, v104
	v_mov_b32_e32 v49, v105
	v_pk_mul_f32 v[32:33], v[32:33], v[66:67] op_sel_hi:[1,0]
	v_pk_mul_f32 v[34:35], v[34:35], v[66:67] op_sel_hi:[1,0]
	v_lshlrev_b32_e32 v52, 16, v48
	v_and_b32_e32 v53, 0xffff0000, v48
	v_lshlrev_b32_e32 v54, 16, v49
	v_and_b32_e32 v55, 0xffff0000, v49
	v_mul_f32_e32 v48, 0xbfb8aa3b, v52
	v_mul_f32_e32 v49, 0xbfb8aa3b, v53
	v_exp_f32_e32 v48, v48
	v_exp_f32_e32 v49, v49
	v_mul_f32_e32 v50, 0xbfb8aa3b, v54
	v_mul_f32_e32 v51, 0xbfb8aa3b, v55
	v_exp_f32_e32 v50, v50
	v_exp_f32_e32 v51, v51
	v_pk_add_f32 v[48:49], v[48:49], 1.0 op_sel_hi:[1,0]
	v_pk_add_f32 v[50:51], v[50:51], 1.0 op_sel_hi:[1,0]
	v_div_scale_f32 v56, s[4:5], v49, v49, v53
	v_div_scale_f32 v58, s[4:5], v48, v48, v52
	v_rcp_f32_e32 v67, v56
	v_div_scale_f32 v60, s[6:7], v51, v51, v55
	v_rcp_f32_e32 v70, v58
	v_div_scale_f32 v62, s[8:9], v50, v50, v54
	v_rcp_f32_e32 v71, v60
	v_rcp_f32_e32 v72, v62
	v_fma_f32 v73, -v56, v67, 1.0
	v_div_scale_f32 v57, vcc, v53, v49, v53
	v_fma_f32 v74, -v58, v70, 1.0
	v_fmac_f32_e32 v67, v73, v67
	v_div_scale_f32 v59, s[4:5], v52, v48, v52
	v_fma_f32 v75, -v60, v71, 1.0
	v_fmac_f32_e32 v70, v74, v70
	v_mul_f32_e32 v73, v57, v67
	v_div_scale_f32 v61, s[6:7], v55, v51, v55
	v_fma_f32 v76, -v62, v72, 1.0
	v_fmac_f32_e32 v71, v75, v71
	v_mul_f32_e32 v74, v59, v70
	v_fma_f32 v77, -v56, v73, v57
	v_div_scale_f32 v63, s[8:9], v54, v50, v54
	v_fmac_f32_e32 v72, v76, v72
	v_mul_f32_e32 v75, v61, v71
	v_fma_f32 v78, -v58, v74, v59
	v_fmac_f32_e32 v73, v77, v67
	v_mul_f32_e32 v76, v63, v72
	v_fma_f32 v79, -v60, v75, v61
	v_fmac_f32_e32 v74, v78, v70
	v_fma_f32 v56, -v56, v73, v57
	v_fma_f32 v80, -v62, v76, v63
	v_fmac_f32_e32 v75, v79, v71
	v_fma_f32 v57, -v58, v74, v59
	v_div_fmas_f32 v56, v56, v67, v73
	s_mov_b64 vcc, s[4:5]
	v_fmac_f32_e32 v76, v80, v72
	v_fma_f32 v58, -v60, v75, v61
	v_div_fixup_f32 v49, v56, v49, v53
	v_div_fmas_f32 v53, v57, v70, v74
	s_mov_b64 vcc, s[6:7]
	v_fma_f32 v59, -v62, v76, v63
	v_div_fixup_f32 v48, v53, v48, v52
	v_div_fmas_f32 v52, v58, v71, v75
	s_mov_b64 vcc, s[8:9]
	v_pk_mul_f32 v[32:33], v[32:33], v[48:49]
	v_div_fmas_f32 v48, v59, v72, v76
	v_div_fixup_f32 v49, v52, v51, v55
	v_div_fixup_f32 v48, v48, v50, v54
	v_pk_mul_f32 v[34:35], v[34:35], v[48:49]
	v_cvt_pk_bf16_f32 v32, v32, v33
	v_cvt_pk_bf16_f32 v33, v34, v35
	v_mov_b32_e32 v128, v32
	v_mov_b32_e32 v129, v33
	v_mov_b32_e32 v32, v106
	v_mov_b32_e32 v33, v107
	v_pk_mul_f32 v[36:37], v[36:37], v[66:67] op_sel_hi:[1,0]
	v_pk_mul_f32 v[38:39], v[38:39], v[66:67] op_sel_hi:[1,0]
	v_lshlrev_b32_e32 v48, 16, v32
	v_and_b32_e32 v49, 0xffff0000, v32
	v_lshlrev_b32_e32 v50, 16, v33
	v_and_b32_e32 v51, 0xffff0000, v33
	v_mul_f32_e32 v32, 0xbfb8aa3b, v48
	v_mul_f32_e32 v33, 0xbfb8aa3b, v49
	v_exp_f32_e32 v32, v32
	v_exp_f32_e32 v33, v33
	v_mul_f32_e32 v34, 0xbfb8aa3b, v50
	v_mul_f32_e32 v35, 0xbfb8aa3b, v51
	v_exp_f32_e32 v34, v34
	v_exp_f32_e32 v35, v35
	v_pk_add_f32 v[32:33], v[32:33], 1.0 op_sel_hi:[1,0]
	v_pk_add_f32 v[34:35], v[34:35], 1.0 op_sel_hi:[1,0]
	v_div_scale_f32 v52, s[4:5], v33, v33, v49
	v_div_scale_f32 v54, s[4:5], v32, v32, v48
	v_rcp_f32_e32 v60, v52
	v_div_scale_f32 v56, s[6:7], v35, v35, v51
	v_rcp_f32_e32 v61, v54
	v_div_scale_f32 v58, s[8:9], v34, v34, v50
	v_rcp_f32_e32 v62, v56
	v_rcp_f32_e32 v63, v58
	v_fma_f32 v67, -v52, v60, 1.0
	v_div_scale_f32 v53, vcc, v49, v33, v49
	v_fma_f32 v70, -v54, v61, 1.0
	v_fmac_f32_e32 v60, v67, v60
	v_div_scale_f32 v55, s[4:5], v48, v32, v48
	v_fma_f32 v71, -v56, v62, 1.0
	v_fmac_f32_e32 v61, v70, v61
	v_mul_f32_e32 v67, v53, v60
	v_div_scale_f32 v57, s[6:7], v51, v35, v51
	v_fma_f32 v72, -v58, v63, 1.0
	v_fmac_f32_e32 v62, v71, v62
	v_mul_f32_e32 v70, v55, v61
	v_fma_f32 v73, -v52, v67, v53
	v_div_scale_f32 v59, s[8:9], v50, v34, v50
	v_fmac_f32_e32 v63, v72, v63
	v_mul_f32_e32 v71, v57, v62
	v_fma_f32 v74, -v54, v70, v55
	v_fmac_f32_e32 v67, v73, v60
	v_mul_f32_e32 v72, v59, v63
	v_fma_f32 v75, -v56, v71, v57
	v_fmac_f32_e32 v70, v74, v61
	v_fma_f32 v52, -v52, v67, v53
	v_fma_f32 v76, -v58, v72, v59
	v_fmac_f32_e32 v71, v75, v62
	v_fma_f32 v53, -v54, v70, v55
	v_div_fmas_f32 v52, v52, v60, v67
	s_mov_b64 vcc, s[4:5]
	v_fmac_f32_e32 v72, v76, v63
	v_fma_f32 v54, -v56, v71, v57
	v_div_fixup_f32 v33, v52, v33, v49
	v_div_fmas_f32 v49, v53, v61, v70
	s_mov_b64 vcc, s[6:7]
	v_fma_f32 v55, -v58, v72, v59
	v_div_fixup_f32 v32, v49, v32, v48
	v_div_fmas_f32 v48, v54, v62, v71
	s_mov_b64 vcc, s[8:9]
	v_pk_mul_f32 v[32:33], v[36:37], v[32:33]
	v_div_fmas_f32 v36, v55, v63, v72
	v_div_fixup_f32 v35, v48, v35, v51
	v_div_fixup_f32 v34, v36, v34, v50
	v_pk_mul_f32 v[34:35], v[38:39], v[34:35]
	v_cvt_pk_bf16_f32 v32, v32, v33
	v_cvt_pk_bf16_f32 v33, v34, v35
	v_mov_b32_e32 v130, v32
	v_mov_b32_e32 v131, v33
	s_nop 1
	v_permlane32_swap_b32_e32 v128, v130
	v_permlane32_swap_b32_e32 v129, v131
	global_store_dwordx4 v[132:133], v[128:131], off offset:64
	v_mov_b32_e32 v32, v108
	v_mov_b32_e32 v33, v109
	v_pk_mul_f32 v[36:37], v[40:41], v[66:67] op_sel_hi:[1,0]
; __device__ __forceinline__ unsigned cvtpk(float lo, float hi) { f32x2 v = {lo, hi}; bf16x2_t b = __builtin_convertvector(v, bf16x2_t); return __builtin_bit_cast(unsigned, b); }
; __device__ __forceinline__ float bf2f(unsigned u16) { return __uint_as_float(u16 << 16); }
; __device__ __forceinline__ float silu(float g) { return g / (1.f + __expf(-g)); }
; template <int MODE>
; __device__ __forceinline__ void attn_unit(const UnitP& P, ALAS char* lds, const float* __restrict__ sub_gain, const int wv0, unsigned& hgen, unsigned* qctr, const int xcd) {
;     ...
; #pragma unroll
;             for (int d0 = 0; d0 < 4; ++d0)
; #pragma unroll
;                 for (int g = 0; g < 4; ++g) {
;                     const u32x2 gg = *(const u32x2*)(gp + 32 * d0 + 8 * g);
;                     const float y0 = o[d0][4 * g + 0] * inv * silu(bf2f(gg.x & 0xffffu)), y1 = o[d0][4 * g + 1] * inv * silu(bf2f(gg.x >> 16));
;                     const float y2 = o[d0][4 * g + 2] * inv * silu(bf2f(gg.y & 0xffffu)), y3 = o[d0][4 * g + 3] * inv * silu(bf2f(gg.y >> 16));
;                     u32x2 w; w.x = cvtpk(y0, y1); w.y = cvtpk(y2, y3);
;                     *(u32x2*)(mp + 32 * d0 + 8 * g) = w;
	v_pk_mul_f32 v[38:39], v[42:43], v[66:67] op_sel_hi:[1,0]
	v_lshlrev_b32_e32 v48, 16, v32
	v_and_b32_e32 v49, 0xffff0000, v32
	v_lshlrev_b32_e32 v50, 16, v33
	v_and_b32_e32 v51, 0xffff0000, v33
	v_mul_f32_e32 v32, 0xbfb8aa3b, v48
	v_mul_f32_e32 v33, 0xbfb8aa3b, v49
	v_exp_f32_e32 v32, v32
	v_exp_f32_e32 v33, v33
	v_mul_f32_e32 v34, 0xbfb8aa3b, v50
	v_mul_f32_e32 v35, 0xbfb8aa3b, v51
	v_exp_f32_e32 v34, v34
	v_exp_f32_e32 v35, v35
	v_pk_add_f32 v[32:33], v[32:33], 1.0 op_sel_hi:[1,0]
	v_pk_add_f32 v[34:35], v[34:35], 1.0 op_sel_hi:[1,0]
	v_div_scale_f32 v40, s[4:5], v33, v33, v49
	v_div_scale_f32 v42, s[4:5], v32, v32, v48
	v_rcp_f32_e32 v56, v40
	v_div_scale_f32 v52, s[6:7], v35, v35, v51
	v_rcp_f32_e32 v57, v42
	v_div_scale_f32 v54, s[8:9], v34, v34, v50
	v_rcp_f32_e32 v58, v52
	v_rcp_f32_e32 v59, v54
	v_fma_f32 v60, -v40, v56, 1.0
	v_div_scale_f32 v41, vcc, v49, v33, v49
	v_fma_f32 v61, -v42, v57, 1.0
	v_fmac_f32_e32 v56, v60, v56
	v_div_scale_f32 v43, s[4:5], v48, v32, v48
	v_fma_f32 v62, -v52, v58, 1.0
	v_fmac_f32_e32 v57, v61, v57
	v_mul_f32_e32 v60, v41, v56
	v_div_scale_f32 v53, s[6:7], v51, v35, v51
	v_fma_f32 v63, -v54, v59, 1.0
	v_fmac_f32_e32 v58, v62, v58
	v_mul_f32_e32 v61, v43, v57
	v_fma_f32 v67, -v40, v60, v41
	v_div_scale_f32 v55, s[8:9], v50, v34, v50
	v_fmac_f32_e32 v59, v63, v59
	v_mul_f32_e32 v62, v53, v58
	v_fma_f32 v70, -v42, v61, v43
	v_fmac_f32_e32 v60, v67, v56
	v_mul_f32_e32 v63, v55, v59
	v_fma_f32 v71, -v52, v62, v53
	v_fmac_f32_e32 v61, v70, v57
	v_fma_f32 v40, -v40, v60, v41
	v_fma_f32 v72, -v54, v63, v55
	v_fmac_f32_e32 v62, v71, v58
	v_fma_f32 v41, -v42, v61, v43
	v_div_fmas_f32 v40, v40, v56, v60
	s_mov_b64 vcc, s[4:5]
	v_fmac_f32_e32 v63, v72, v59
	v_fma_f32 v42, -v52, v62, v53
	v_div_fixup_f32 v33, v40, v33, v49
	v_div_fmas_f32 v40, v41, v57, v61
	s_mov_b64 vcc, s[6:7]
	v_fma_f32 v43, -v54, v63, v55
	v_div_fixup_f32 v32, v40, v32, v48
	v_div_fmas_f32 v40, v42, v58, v62
	s_mov_b64 vcc, s[8:9]
	v_pk_mul_f32 v[32:33], v[36:37], v[32:33]
	v_div_fmas_f32 v36, v43, v59, v63
	v_div_fixup_f32 v35, v40, v35, v51
	v_div_fixup_f32 v34, v36, v34, v50
	v_pk_mul_f32 v[34:35], v[38:39], v[34:35]
	v_cvt_pk_bf16_f32 v32, v32, v33
	v_cvt_pk_bf16_f32 v33, v34, v35
	v_mov_b32_e32 v128, v32
	v_mov_b32_e32 v129, v33
	v_mov_b32_e32 v32, v110
	v_mov_b32_e32 v33, v111
	v_pk_mul_f32 v[36:37], v[44:45], v[66:67] op_sel_hi:[1,0]
	v_pk_mul_f32 v[38:39], v[46:47], v[66:67] op_sel_hi:[1,0]
	v_pk_mul_f32 v[16:17], v[16:17], v[66:67] op_sel_hi:[1,0]
	v_pk_mul_f32 v[18:19], v[18:19], v[66:67] op_sel_hi:[1,0]
	v_pk_mul_f32 v[20:21], v[20:21], v[66:67] op_sel_hi:[1,0]
	v_pk_mul_f32 v[22:23], v[22:23], v[66:67] op_sel_hi:[1,0]
	v_pk_mul_f32 v[0:1], v[0:1], v[66:67] op_sel_hi:[1,0]
	v_pk_mul_f32 v[2:3], v[2:3], v[66:67] op_sel_hi:[1,0]
	v_pk_mul_f32 v[4:5], v[4:5], v[66:67] op_sel_hi:[1,0]
	v_pk_mul_f32 v[6:7], v[6:7], v[66:67] op_sel_hi:[1,0]
	v_lshlrev_b32_e32 v40, 16, v32
	v_and_b32_e32 v41, 0xffff0000, v32
	v_lshlrev_b32_e32 v42, 16, v33
	v_and_b32_e32 v43, 0xffff0000, v33
	v_mul_f32_e32 v32, 0xbfb8aa3b, v40
	v_mul_f32_e32 v33, 0xbfb8aa3b, v41
	v_exp_f32_e32 v32, v32
	v_exp_f32_e32 v33, v33
	v_mul_f32_e32 v34, 0xbfb8aa3b, v42
	v_mul_f32_e32 v35, 0xbfb8aa3b, v43
	v_exp_f32_e32 v34, v34
	v_exp_f32_e32 v35, v35
	v_pk_add_f32 v[32:33], v[32:33], 1.0 op_sel_hi:[1,0]
	v_pk_add_f32 v[34:35], v[34:35], 1.0 op_sel_hi:[1,0]
	v_div_scale_f32 v44, s[4:5], v33, v33, v41
	v_div_scale_f32 v46, s[4:5], v32, v32, v40
	v_rcp_f32_e32 v52, v44
	v_div_scale_f32 v48, s[6:7], v35, v35, v43
	v_rcp_f32_e32 v53, v46
	v_div_scale_f32 v50, s[8:9], v34, v34, v42
	v_rcp_f32_e32 v54, v48
	v_rcp_f32_e32 v55, v50
	v_fma_f32 v56, -v44, v52, 1.0
	v_div_scale_f32 v45, vcc, v41, v33, v41
	v_fma_f32 v57, -v46, v53, 1.0
	v_fmac_f32_e32 v52, v56, v52
	v_div_scale_f32 v47, s[4:5], v40, v32, v40
	v_fma_f32 v58, -v48, v54, 1.0
	v_fmac_f32_e32 v53, v57, v53
	v_mul_f32_e32 v56, v45, v52
	v_div_scale_f32 v49, s[6:7], v43, v35, v43
	v_fma_f32 v59, -v50, v55, 1.0
	v_fmac_f32_e32 v54, v58, v54
	v_mul_f32_e32 v57, v47, v53
	v_fma_f32 v60, -v44, v56, v45
	v_div_scale_f32 v51, s[8:9], v42, v34, v42
	v_fmac_f32_e32 v55, v59, v55
	v_mul_f32_e32 v58, v49, v54
	v_fma_f32 v61, -v46, v57, v47
	v_fmac_f32_e32 v56, v60, v52
	v_mul_f32_e32 v59, v51, v55
	v_fma_f32 v62, -v48, v58, v49
	v_fmac_f32_e32 v57, v61, v53
	v_fma_f32 v44, -v44, v56, v45
	v_fma_f32 v63, -v50, v59, v51
	v_fmac_f32_e32 v58, v62, v54
	v_fma_f32 v45, -v46, v57, v47
	v_div_fmas_f32 v44, v44, v52, v56
	s_mov_b64 vcc, s[4:5]
	v_fmac_f32_e32 v59, v63, v55
	v_fma_f32 v46, -v48, v58, v49
	v_div_fixup_f32 v33, v44, v33, v41
	v_div_fmas_f32 v41, v45, v53, v57
	s_mov_b64 vcc, s[6:7]
	v_fma_f32 v47, -v50, v59, v51
	v_div_fixup_f32 v32, v41, v32, v40
	v_div_fmas_f32 v40, v46, v54, v58
	s_mov_b64 vcc, s[8:9]
	v_pk_mul_f32 v[32:33], v[36:37], v[32:33]
	v_div_fmas_f32 v36, v47, v55, v59
	v_div_fixup_f32 v35, v40, v35, v43
	v_div_fixup_f32 v34, v36, v34, v42
	v_pk_mul_f32 v[34:35], v[38:39], v[34:35]
	v_cvt_pk_bf16_f32 v32, v32, v33
	v_cvt_pk_bf16_f32 v33, v34, v35
	v_mov_b32_e32 v130, v32
	v_mov_b32_e32 v131, v33
	s_nop 1
	v_permlane32_swap_b32_e32 v128, v130
	v_permlane32_swap_b32_e32 v129, v131
	global_store_dwordx4 v[132:133], v[128:131], off offset:96
	v_mov_b32_e32 v32, v112
	v_mov_b32_e32 v33, v113
	v_lshlrev_b32_e32 v36, 16, v32
	v_and_b32_e32 v37, 0xffff0000, v32
	v_lshlrev_b32_e32 v38, 16, v33
	v_and_b32_e32 v39, 0xffff0000, v33
	v_mul_f32_e32 v32, 0xbfb8aa3b, v36
	v_mul_f32_e32 v33, 0xbfb8aa3b, v37
	v_exp_f32_e32 v32, v32
	v_exp_f32_e32 v33, v33
	v_mul_f32_e32 v34, 0xbfb8aa3b, v38
	v_mul_f32_e32 v35, 0xbfb8aa3b, v39
; __device__ __forceinline__ unsigned cvtpk(float lo, float hi) { f32x2 v = {lo, hi}; bf16x2_t b = __builtin_convertvector(v, bf16x2_t); return __builtin_bit_cast(unsigned, b); }
; __device__ __forceinline__ float bf2f(unsigned u16) { return __uint_as_float(u16 << 16); }
; __device__ __forceinline__ float silu(float g) { return g / (1.f + __expf(-g)); }
; template <int MODE>
; __device__ __forceinline__ void attn_unit(const UnitP& P, ALAS char* lds, const float* __restrict__ sub_gain, const int wv0, unsigned& hgen, unsigned* qctr, const int xcd) {
;     ...
; #pragma unroll
;             for (int d0 = 0; d0 < 4; ++d0)
; #pragma unroll
;                 for (int g = 0; g < 4; ++g) {
;                     const u32x2 gg = *(const u32x2*)(gp + 32 * d0 + 8 * g);
;                     const float y0 = o[d0][4 * g + 0] * inv * silu(bf2f(gg.x & 0xffffu)), y1 = o[d0][4 * g + 1] * inv * silu(bf2f(gg.x >> 16));
;                     const float y2 = o[d0][4 * g + 2] * inv * silu(bf2f(gg.y & 0xffffu)), y3 = o[d0][4 * g + 3] * inv * silu(bf2f(gg.y >> 16));
;                     u32x2 w; w.x = cvtpk(y0, y1); w.y = cvtpk(y2, y3);
;                     *(u32x2*)(mp + 32 * d0 + 8 * g) = w;
	v_exp_f32_e32 v34, v34
	v_exp_f32_e32 v35, v35
	v_pk_add_f32 v[32:33], v[32:33], 1.0 op_sel_hi:[1,0]
	v_pk_add_f32 v[34:35], v[34:35], 1.0 op_sel_hi:[1,0]
	v_div_scale_f32 v40, s[4:5], v33, v33, v37
	v_div_scale_f32 v42, s[4:5], v32, v32, v36
	v_rcp_f32_e32 v48, v40
	v_div_scale_f32 v44, s[6:7], v35, v35, v39
	v_rcp_f32_e32 v49, v42
	v_div_scale_f32 v46, s[8:9], v34, v34, v38
	v_rcp_f32_e32 v50, v44
	v_rcp_f32_e32 v51, v46
	v_fma_f32 v52, -v40, v48, 1.0
	v_div_scale_f32 v41, vcc, v37, v33, v37
	v_fma_f32 v53, -v42, v49, 1.0
	v_fmac_f32_e32 v48, v52, v48
	v_div_scale_f32 v43, s[4:5], v36, v32, v36
	v_fma_f32 v54, -v44, v50, 1.0
	v_fmac_f32_e32 v49, v53, v49
	v_mul_f32_e32 v52, v41, v48
	v_div_scale_f32 v45, s[6:7], v39, v35, v39
	v_fma_f32 v55, -v46, v51, 1.0
	v_fmac_f32_e32 v50, v54, v50
	v_mul_f32_e32 v53, v43, v49
	v_fma_f32 v56, -v40, v52, v41
	v_div_scale_f32 v47, s[8:9], v38, v34, v38
	v_fmac_f32_e32 v51, v55, v51
	v_mul_f32_e32 v54, v45, v50
	v_fma_f32 v57, -v42, v53, v43
	v_fmac_f32_e32 v52, v56, v48
	v_mul_f32_e32 v55, v47, v51
	v_fma_f32 v58, -v44, v54, v45
	v_fmac_f32_e32 v53, v57, v49
	v_fma_f32 v40, -v40, v52, v41
	v_fma_f32 v59, -v46, v55, v47
	v_fmac_f32_e32 v54, v58, v50
	v_fma_f32 v41, -v42, v53, v43
	v_div_fmas_f32 v40, v40, v48, v52
	s_mov_b64 vcc, s[4:5]
	v_fmac_f32_e32 v55, v59, v51
	v_fma_f32 v42, -v44, v54, v45
	v_div_fixup_f32 v33, v40, v33, v37
	v_div_fmas_f32 v37, v41, v49, v53
	s_mov_b64 vcc, s[6:7]
	v_fma_f32 v43, -v46, v55, v47
	v_div_fixup_f32 v32, v37, v32, v36
	v_div_fmas_f32 v36, v42, v50, v54
	s_mov_b64 vcc, s[8:9]
	v_pk_mul_f32 v[16:17], v[16:17], v[32:33]
	v_div_fmas_f32 v32, v43, v51, v55
	v_div_fixup_f32 v33, v36, v35, v39
	v_div_fixup_f32 v32, v32, v34, v38
	v_pk_mul_f32 v[18:19], v[18:19], v[32:33]
	v_cvt_pk_bf16_f32 v16, v16, v17
	v_cvt_pk_bf16_f32 v17, v18, v19
	v_mov_b32_e32 v128, v16
	v_mov_b32_e32 v129, v17
	v_mov_b32_e32 v16, v114
	v_mov_b32_e32 v17, v115
	v_lshlrev_b32_e32 v32, 16, v16
	v_and_b32_e32 v33, 0xffff0000, v16
	v_lshlrev_b32_e32 v34, 16, v17
	v_and_b32_e32 v35, 0xffff0000, v17
	v_mul_f32_e32 v16, 0xbfb8aa3b, v32
	v_mul_f32_e32 v17, 0xbfb8aa3b, v33
	v_exp_f32_e32 v16, v16
	v_exp_f32_e32 v17, v17
	v_mul_f32_e32 v18, 0xbfb8aa3b, v34
	v_mul_f32_e32 v19, 0xbfb8aa3b, v35
	v_exp_f32_e32 v18, v18
	v_exp_f32_e32 v19, v19
	v_pk_add_f32 v[16:17], v[16:17], 1.0 op_sel_hi:[1,0]
	v_pk_add_f32 v[18:19], v[18:19], 1.0 op_sel_hi:[1,0]
	v_div_scale_f32 v36, s[4:5], v17, v17, v33
	v_div_scale_f32 v38, s[4:5], v16, v16, v32
	v_rcp_f32_e32 v44, v36
	v_div_scale_f32 v40, s[6:7], v19, v19, v35
	v_rcp_f32_e32 v45, v38
	v_div_scale_f32 v42, s[8:9], v18, v18, v34
	v_rcp_f32_e32 v46, v40
	v_rcp_f32_e32 v47, v42
	v_fma_f32 v48, -v36, v44, 1.0
	v_div_scale_f32 v37, vcc, v33, v17, v33
	v_fma_f32 v49, -v38, v45, 1.0
	v_fmac_f32_e32 v44, v48, v44
	v_div_scale_f32 v39, s[4:5], v32, v16, v32
	v_fma_f32 v50, -v40, v46, 1.0
	v_fmac_f32_e32 v45, v49, v45
	v_mul_f32_e32 v48, v37, v44
	v_div_scale_f32 v41, s[6:7], v35, v19, v35
	v_fma_f32 v51, -v42, v47, 1.0
	v_fmac_f32_e32 v46, v50, v46
	v_mul_f32_e32 v49, v39, v45
	v_fma_f32 v52, -v36, v48, v37
	v_div_scale_f32 v43, s[8:9], v34, v18, v34
	v_fmac_f32_e32 v47, v51, v47
	v_mul_f32_e32 v50, v41, v46
	v_fma_f32 v53, -v38, v49, v39
	v_fmac_f32_e32 v48, v52, v44
	v_mul_f32_e32 v51, v43, v47
	v_fma_f32 v54, -v40, v50, v41
	v_fmac_f32_e32 v49, v53, v45
	v_fma_f32 v36, -v36, v48, v37
	v_fma_f32 v55, -v42, v51, v43
	v_fmac_f32_e32 v50, v54, v46
	v_fma_f32 v37, -v38, v49, v39
	v_div_fmas_f32 v36, v36, v44, v48
	s_mov_b64 vcc, s[4:5]
	v_fmac_f32_e32 v51, v55, v47
	v_fma_f32 v38, -v40, v50, v41
	v_div_fixup_f32 v17, v36, v17, v33
	v_div_fmas_f32 v33, v37, v45, v49
	s_mov_b64 vcc, s[6:7]
	v_fma_f32 v39, -v42, v51, v43
	v_div_fixup_f32 v16, v33, v16, v32
	v_div_fmas_f32 v32, v38, v46, v50
	s_mov_b64 vcc, s[8:9]
	v_pk_mul_f32 v[16:17], v[20:21], v[16:17]
	v_div_fmas_f32 v20, v39, v47, v51
	v_div_fixup_f32 v19, v32, v19, v35
	v_div_fixup_f32 v18, v20, v18, v34
	v_pk_mul_f32 v[18:19], v[22:23], v[18:19]
	v_cvt_pk_bf16_f32 v16, v16, v17
	v_cvt_pk_bf16_f32 v17, v18, v19
	v_mov_b32_e32 v130, v16
	v_mov_b32_e32 v131, v17
	s_nop 1
	v_permlane32_swap_b32_e32 v128, v130
	v_permlane32_swap_b32_e32 v129, v131
	global_store_dwordx4 v[132:133], v[128:131], off offset:128
	v_mov_b32_e32 v16, v116
	v_mov_b32_e32 v17, v117
	v_pk_mul_f32 v[20:21], v[24:25], v[66:67] op_sel_hi:[1,0]
	v_pk_mul_f32 v[22:23], v[26:27], v[66:67] op_sel_hi:[1,0]
	v_lshlrev_b32_e32 v32, 16, v16
	v_and_b32_e32 v33, 0xffff0000, v16
	v_lshlrev_b32_e32 v34, 16, v17
	v_and_b32_e32 v35, 0xffff0000, v17
	v_mul_f32_e32 v16, 0xbfb8aa3b, v32
	v_mul_f32_e32 v17, 0xbfb8aa3b, v33
	v_exp_f32_e32 v16, v16
	v_exp_f32_e32 v17, v17
	v_mul_f32_e32 v18, 0xbfb8aa3b, v34
	v_mul_f32_e32 v19, 0xbfb8aa3b, v35
	v_exp_f32_e32 v18, v18
	v_exp_f32_e32 v19, v19
	v_pk_add_f32 v[16:17], v[16:17], 1.0 op_sel_hi:[1,0]
	v_pk_add_f32 v[18:19], v[18:19], 1.0 op_sel_hi:[1,0]
	v_div_scale_f32 v24, s[4:5], v17, v17, v33
	v_div_scale_f32 v26, s[4:5], v16, v16, v32
	v_rcp_f32_e32 v40, v24
	v_div_scale_f32 v36, s[6:7], v19, v19, v35
	v_rcp_f32_e32 v41, v26
	v_div_scale_f32 v38, s[8:9], v18, v18, v34
	v_rcp_f32_e32 v42, v36
	v_rcp_f32_e32 v43, v38
	v_fma_f32 v44, -v24, v40, 1.0
	v_div_scale_f32 v25, vcc, v33, v17, v33
	v_fma_f32 v45, -v26, v41, 1.0
	v_fmac_f32_e32 v40, v44, v40
	v_div_scale_f32 v27, s[4:5], v32, v16, v32
	v_fma_f32 v46, -v36, v42, 1.0
	v_fmac_f32_e32 v41, v45, v41
	v_mul_f32_e32 v44, v25, v40
	v_div_scale_f32 v37, s[6:7], v35, v19, v35
	v_fma_f32 v47, -v38, v43, 1.0
	v_fmac_f32_e32 v42, v46, v42
	v_mul_f32_e32 v45, v27, v41
	v_fma_f32 v48, -v24, v44, v25
; __device__ __forceinline__ unsigned cvtpk(float lo, float hi) { f32x2 v = {lo, hi}; bf16x2_t b = __builtin_convertvector(v, bf16x2_t); return __builtin_bit_cast(unsigned, b); }
; __device__ __forceinline__ float bf2f(unsigned u16) { return __uint_as_float(u16 << 16); }
; __device__ __forceinline__ float silu(float g) { return g / (1.f + __expf(-g)); }
; template <int MODE>
; __device__ __forceinline__ void attn_unit(const UnitP& P, ALAS char* lds, const float* __restrict__ sub_gain, const int wv0, unsigned& hgen, unsigned* qctr, const int xcd) {
;     ...
; #pragma unroll
;             for (int d0 = 0; d0 < 4; ++d0)
; #pragma unroll
;                 for (int g = 0; g < 4; ++g) {
;                     const u32x2 gg = *(const u32x2*)(gp + 32 * d0 + 8 * g);
;                     const float y0 = o[d0][4 * g + 0] * inv * silu(bf2f(gg.x & 0xffffu)), y1 = o[d0][4 * g + 1] * inv * silu(bf2f(gg.x >> 16));
;                     const float y2 = o[d0][4 * g + 2] * inv * silu(bf2f(gg.y & 0xffffu)), y3 = o[d0][4 * g + 3] * inv * silu(bf2f(gg.y >> 16));
;                     u32x2 w; w.x = cvtpk(y0, y1); w.y = cvtpk(y2, y3);
;                     *(u32x2*)(mp + 32 * d0 + 8 * g) = w;
	v_div_scale_f32 v39, s[8:9], v34, v18, v34
	v_fmac_f32_e32 v43, v47, v43
	v_mul_f32_e32 v46, v37, v42
	v_fma_f32 v49, -v26, v45, v27
	v_fmac_f32_e32 v44, v48, v40
	v_mul_f32_e32 v47, v39, v43
	v_fma_f32 v50, -v36, v46, v37
	v_fmac_f32_e32 v45, v49, v41
	v_fma_f32 v24, -v24, v44, v25
	v_fma_f32 v51, -v38, v47, v39
	v_fmac_f32_e32 v46, v50, v42
	v_fma_f32 v25, -v26, v45, v27
	v_div_fmas_f32 v24, v24, v40, v44
	s_mov_b64 vcc, s[4:5]
	v_fmac_f32_e32 v47, v51, v43
	v_fma_f32 v26, -v36, v46, v37
	v_div_fixup_f32 v17, v24, v17, v33
	v_div_fmas_f32 v24, v25, v41, v45
	s_mov_b64 vcc, s[6:7]
	v_fma_f32 v27, -v38, v47, v39
	v_div_fixup_f32 v16, v24, v16, v32
	v_div_fmas_f32 v24, v26, v42, v46
	s_mov_b64 vcc, s[8:9]
	v_pk_mul_f32 v[16:17], v[20:21], v[16:17]
	v_div_fmas_f32 v20, v27, v43, v47
	v_div_fixup_f32 v19, v24, v19, v35
	v_div_fixup_f32 v18, v20, v18, v34
	v_pk_mul_f32 v[18:19], v[22:23], v[18:19]
	v_cvt_pk_bf16_f32 v16, v16, v17
	v_cvt_pk_bf16_f32 v17, v18, v19
	v_mov_b32_e32 v128, v16
	v_mov_b32_e32 v129, v17
	v_mov_b32_e32 v16, v118
	v_mov_b32_e32 v17, v119
	v_pk_mul_f32 v[20:21], v[28:29], v[66:67] op_sel_hi:[1,0]
	v_pk_mul_f32 v[22:23], v[30:31], v[66:67] op_sel_hi:[1,0]
	v_lshlrev_b32_e32 v24, 16, v16
	v_and_b32_e32 v25, 0xffff0000, v16
	v_lshlrev_b32_e32 v26, 16, v17
	v_and_b32_e32 v27, 0xffff0000, v17
	v_mul_f32_e32 v16, 0xbfb8aa3b, v24
	v_mul_f32_e32 v17, 0xbfb8aa3b, v25
	v_exp_f32_e32 v16, v16
	v_exp_f32_e32 v17, v17
	v_mul_f32_e32 v18, 0xbfb8aa3b, v26
	v_mul_f32_e32 v19, 0xbfb8aa3b, v27
	v_exp_f32_e32 v18, v18
	v_exp_f32_e32 v19, v19
	v_pk_add_f32 v[16:17], v[16:17], 1.0 op_sel_hi:[1,0]
	v_pk_add_f32 v[18:19], v[18:19], 1.0 op_sel_hi:[1,0]
	v_div_scale_f32 v28, s[4:5], v17, v17, v25
	v_div_scale_f32 v30, s[4:5], v16, v16, v24
	v_rcp_f32_e32 v36, v28
	v_div_scale_f32 v32, s[6:7], v19, v19, v27
	v_rcp_f32_e32 v37, v30
	v_div_scale_f32 v34, s[8:9], v18, v18, v26
	v_rcp_f32_e32 v38, v32
	v_rcp_f32_e32 v39, v34
	v_fma_f32 v40, -v28, v36, 1.0
	v_div_scale_f32 v29, vcc, v25, v17, v25
	v_fma_f32 v41, -v30, v37, 1.0
	v_fmac_f32_e32 v36, v40, v36
	v_div_scale_f32 v31, s[4:5], v24, v16, v24
	v_fma_f32 v42, -v32, v38, 1.0
	v_fmac_f32_e32 v37, v41, v37
	v_mul_f32_e32 v40, v29, v36
	v_div_scale_f32 v33, s[6:7], v27, v19, v27
	v_fma_f32 v43, -v34, v39, 1.0
	v_fmac_f32_e32 v38, v42, v38
	v_mul_f32_e32 v41, v31, v37
	v_fma_f32 v44, -v28, v40, v29
	v_div_scale_f32 v35, s[8:9], v26, v18, v26
	v_fmac_f32_e32 v39, v43, v39
	v_mul_f32_e32 v42, v33, v38
	v_fma_f32 v45, -v30, v41, v31
	v_fmac_f32_e32 v40, v44, v36
	v_mul_f32_e32 v43, v35, v39
	v_fma_f32 v46, -v32, v42, v33
	v_fmac_f32_e32 v41, v45, v37
	v_fma_f32 v28, -v28, v40, v29
	v_fma_f32 v47, -v34, v43, v35
	v_fmac_f32_e32 v42, v46, v38
	v_fma_f32 v29, -v30, v41, v31
	v_div_fmas_f32 v28, v28, v36, v40
	s_mov_b64 vcc, s[4:5]
	v_fmac_f32_e32 v43, v47, v39
	v_fma_f32 v30, -v32, v42, v33
	v_div_fixup_f32 v17, v28, v17, v25
	v_div_fmas_f32 v25, v29, v37, v41
	s_mov_b64 vcc, s[6:7]
	v_fma_f32 v31, -v34, v43, v35
	v_div_fixup_f32 v16, v25, v16, v24
	v_div_fmas_f32 v24, v30, v38, v42
	s_mov_b64 vcc, s[8:9]
	v_pk_mul_f32 v[16:17], v[20:21], v[16:17]
	v_div_fmas_f32 v20, v31, v39, v43
	v_div_fixup_f32 v19, v24, v19, v27
	v_div_fixup_f32 v18, v20, v18, v26
	v_pk_mul_f32 v[18:19], v[22:23], v[18:19]
	v_cvt_pk_bf16_f32 v16, v16, v17
	v_cvt_pk_bf16_f32 v17, v18, v19
	v_mov_b32_e32 v130, v16
	v_mov_b32_e32 v131, v17
	s_nop 1
	v_permlane32_swap_b32_e32 v128, v130
	v_permlane32_swap_b32_e32 v129, v131
	global_store_dwordx4 v[132:133], v[128:131], off offset:160
	v_mov_b32_e32 v16, v120
	v_mov_b32_e32 v17, v121
	v_lshlrev_b32_e32 v20, 16, v16
	v_and_b32_e32 v21, 0xffff0000, v16
	v_lshlrev_b32_e32 v22, 16, v17
	v_and_b32_e32 v23, 0xffff0000, v17
	v_mul_f32_e32 v16, 0xbfb8aa3b, v20
	v_mul_f32_e32 v17, 0xbfb8aa3b, v21
	v_exp_f32_e32 v16, v16
	v_exp_f32_e32 v17, v17
	v_mul_f32_e32 v18, 0xbfb8aa3b, v22
	v_mul_f32_e32 v19, 0xbfb8aa3b, v23
	v_exp_f32_e32 v18, v18
	v_exp_f32_e32 v19, v19
	v_pk_add_f32 v[16:17], v[16:17], 1.0 op_sel_hi:[1,0]
	v_pk_add_f32 v[18:19], v[18:19], 1.0 op_sel_hi:[1,0]
	v_div_scale_f32 v24, s[4:5], v17, v17, v21
	v_div_scale_f32 v26, s[4:5], v16, v16, v20
	v_rcp_f32_e32 v32, v24
	v_div_scale_f32 v28, s[6:7], v19, v19, v23
	v_rcp_f32_e32 v33, v26
	v_div_scale_f32 v30, s[8:9], v18, v18, v22
	v_rcp_f32_e32 v34, v28
	v_rcp_f32_e32 v35, v30
	v_fma_f32 v36, -v24, v32, 1.0
	v_div_scale_f32 v25, vcc, v21, v17, v21
	v_fma_f32 v37, -v26, v33, 1.0
	v_fmac_f32_e32 v32, v36, v32
	v_div_scale_f32 v27, s[4:5], v20, v16, v20
	v_fma_f32 v38, -v28, v34, 1.0
	v_fmac_f32_e32 v33, v37, v33
	v_mul_f32_e32 v36, v25, v32
	v_div_scale_f32 v29, s[6:7], v23, v19, v23
	v_fma_f32 v39, -v30, v35, 1.0
	v_fmac_f32_e32 v34, v38, v34
	v_mul_f32_e32 v37, v27, v33
	v_fma_f32 v40, -v24, v36, v25
	v_div_scale_f32 v31, s[8:9], v22, v18, v22
	v_fmac_f32_e32 v35, v39, v35
	v_mul_f32_e32 v38, v29, v34
	v_fma_f32 v41, -v26, v37, v27
	v_fmac_f32_e32 v36, v40, v32
	v_mul_f32_e32 v39, v31, v35
	v_fma_f32 v42, -v28, v38, v29
	v_fmac_f32_e32 v37, v41, v33
	v_fma_f32 v24, -v24, v36, v25
	v_fma_f32 v43, -v30, v39, v31
	v_fmac_f32_e32 v38, v42, v34
	v_fma_f32 v25, -v26, v37, v27
	v_div_fmas_f32 v24, v24, v32, v36
	s_mov_b64 vcc, s[4:5]
	v_fmac_f32_e32 v39, v43, v35
	v_fma_f32 v26, -v28, v38, v29
	v_div_fixup_f32 v17, v24, v17, v21
	v_div_fmas_f32 v21, v25, v33, v37
	s_mov_b64 vcc, s[6:7]
	v_fma_f32 v27, -v30, v39, v31
	v_div_fixup_f32 v16, v21, v16, v20
	v_div_fmas_f32 v20, v26, v34, v38
	s_mov_b64 vcc, s[8:9]
	v_pk_mul_f32 v[0:1], v[0:1], v[16:17]
	v_div_fmas_f32 v16, v27, v35, v39
	v_div_fixup_f32 v17, v20, v19, v23
	v_div_fixup_f32 v16, v16, v18, v22
; __device__ __forceinline__ unsigned cvtpk(float lo, float hi) { f32x2 v = {lo, hi}; bf16x2_t b = __builtin_convertvector(v, bf16x2_t); return __builtin_bit_cast(unsigned, b); }
; __device__ __forceinline__ float bf2f(unsigned u16) { return __uint_as_float(u16 << 16); }
; __device__ __forceinline__ float silu(float g) { return g / (1.f + __expf(-g)); }
; template <int MODE>
; __device__ __forceinline__ void attn_unit(const UnitP& P, ALAS char* lds, const float* __restrict__ sub_gain, const int wv0, unsigned& hgen, unsigned* qctr, const int xcd) {
;     ...
; #pragma unroll
;             for (int d0 = 0; d0 < 4; ++d0)
; #pragma unroll
;                 for (int g = 0; g < 4; ++g) {
;                     const u32x2 gg = *(const u32x2*)(gp + 32 * d0 + 8 * g);
;                     const float y0 = o[d0][4 * g + 0] * inv * silu(bf2f(gg.x & 0xffffu)), y1 = o[d0][4 * g + 1] * inv * silu(bf2f(gg.x >> 16));
;                     const float y2 = o[d0][4 * g + 2] * inv * silu(bf2f(gg.y & 0xffffu)), y3 = o[d0][4 * g + 3] * inv * silu(bf2f(gg.y >> 16));
;                     u32x2 w; w.x = cvtpk(y0, y1); w.y = cvtpk(y2, y3);
;                     *(u32x2*)(mp + 32 * d0 + 8 * g) = w;
	v_pk_mul_f32 v[2:3], v[2:3], v[16:17]
	v_cvt_pk_bf16_f32 v0, v0, v1
	v_cvt_pk_bf16_f32 v1, v2, v3
	v_mov_b32_e32 v128, v0
	v_mov_b32_e32 v129, v1
	v_mov_b32_e32 v0, v122
	v_mov_b32_e32 v1, v123
	v_lshlrev_b32_e32 v16, 16, v0
	v_and_b32_e32 v17, 0xffff0000, v0
	v_lshlrev_b32_e32 v18, 16, v1
	v_and_b32_e32 v19, 0xffff0000, v1
	v_mul_f32_e32 v0, 0xbfb8aa3b, v16
	v_mul_f32_e32 v1, 0xbfb8aa3b, v17
	v_exp_f32_e32 v0, v0
	v_exp_f32_e32 v1, v1
	v_mul_f32_e32 v2, 0xbfb8aa3b, v18
	v_mul_f32_e32 v3, 0xbfb8aa3b, v19
	v_exp_f32_e32 v2, v2
	v_exp_f32_e32 v3, v3
	v_pk_add_f32 v[0:1], v[0:1], 1.0 op_sel_hi:[1,0]
	v_pk_add_f32 v[2:3], v[2:3], 1.0 op_sel_hi:[1,0]
	v_div_scale_f32 v20, s[4:5], v1, v1, v17
	v_div_scale_f32 v22, s[4:5], v0, v0, v16
	v_rcp_f32_e32 v28, v20
	v_div_scale_f32 v24, s[6:7], v3, v3, v19
	v_rcp_f32_e32 v29, v22
	v_div_scale_f32 v26, s[8:9], v2, v2, v18
	v_rcp_f32_e32 v30, v24
	v_rcp_f32_e32 v31, v26
	v_fma_f32 v32, -v20, v28, 1.0
	v_div_scale_f32 v21, vcc, v17, v1, v17
	v_fma_f32 v33, -v22, v29, 1.0
	v_fmac_f32_e32 v28, v32, v28
	v_div_scale_f32 v23, s[4:5], v16, v0, v16
	v_fma_f32 v34, -v24, v30, 1.0
	v_fmac_f32_e32 v29, v33, v29
	v_mul_f32_e32 v32, v21, v28
	v_div_scale_f32 v25, s[6:7], v19, v3, v19
	v_fma_f32 v35, -v26, v31, 1.0
	v_fmac_f32_e32 v30, v34, v30
	v_mul_f32_e32 v33, v23, v29
	v_fma_f32 v36, -v20, v32, v21
	v_div_scale_f32 v27, s[8:9], v18, v2, v18
	v_fmac_f32_e32 v31, v35, v31
	v_mul_f32_e32 v34, v25, v30
	v_fma_f32 v37, -v22, v33, v23
	v_fmac_f32_e32 v32, v36, v28
	v_mul_f32_e32 v35, v27, v31
	v_fma_f32 v38, -v24, v34, v25
	v_fmac_f32_e32 v33, v37, v29
	v_fma_f32 v20, -v20, v32, v21
	v_fma_f32 v39, -v26, v35, v27
	v_fmac_f32_e32 v34, v38, v30
	v_fma_f32 v21, -v22, v33, v23
	v_div_fmas_f32 v20, v20, v28, v32
	s_mov_b64 vcc, s[4:5]
	v_fmac_f32_e32 v35, v39, v31
	v_fma_f32 v22, -v24, v34, v25
	v_div_fixup_f32 v1, v20, v1, v17
	v_div_fmas_f32 v17, v21, v29, v33
	s_mov_b64 vcc, s[6:7]
	v_fma_f32 v23, -v26, v35, v27
	v_div_fixup_f32 v0, v17, v0, v16
	v_div_fmas_f32 v16, v22, v30, v34
	s_mov_b64 vcc, s[8:9]
	v_pk_mul_f32 v[0:1], v[4:5], v[0:1]
	v_div_fmas_f32 v4, v23, v31, v35
	v_div_fixup_f32 v3, v16, v3, v19
	v_div_fixup_f32 v2, v4, v2, v18
	v_pk_mul_f32 v[2:3], v[6:7], v[2:3]
	v_cvt_pk_bf16_f32 v0, v0, v1
	v_cvt_pk_bf16_f32 v1, v2, v3
	v_mov_b32_e32 v130, v0
	v_mov_b32_e32 v131, v1
	s_nop 1
	v_permlane32_swap_b32_e32 v128, v130
	v_permlane32_swap_b32_e32 v129, v131
	global_store_dwordx4 v[132:133], v[128:131], off offset:192
	v_mov_b32_e32 v0, v124
	v_mov_b32_e32 v1, v125
	v_pk_mul_f32 v[4:5], v[8:9], v[66:67] op_sel_hi:[1,0]
	v_pk_mul_f32 v[6:7], v[10:11], v[66:67] op_sel_hi:[1,0]
	v_lshlrev_b32_e32 v16, 16, v0
	v_and_b32_e32 v17, 0xffff0000, v0
	v_lshlrev_b32_e32 v18, 16, v1
	v_and_b32_e32 v19, 0xffff0000, v1
	v_mul_f32_e32 v0, 0xbfb8aa3b, v16
	v_mul_f32_e32 v1, 0xbfb8aa3b, v17
	v_exp_f32_e32 v0, v0
	v_exp_f32_e32 v1, v1
	v_mul_f32_e32 v2, 0xbfb8aa3b, v18
	v_mul_f32_e32 v3, 0xbfb8aa3b, v19
	v_exp_f32_e32 v2, v2
	v_exp_f32_e32 v3, v3
	v_pk_add_f32 v[0:1], v[0:1], 1.0 op_sel_hi:[1,0]
	v_pk_add_f32 v[2:3], v[2:3], 1.0 op_sel_hi:[1,0]
	v_div_scale_f32 v8, s[4:5], v1, v1, v17
	v_div_scale_f32 v10, s[4:5], v0, v0, v16
	v_rcp_f32_e32 v24, v8
	v_div_scale_f32 v20, s[6:7], v3, v3, v19
	v_rcp_f32_e32 v25, v10
	v_div_scale_f32 v22, s[8:9], v2, v2, v18
	v_rcp_f32_e32 v26, v20
	v_rcp_f32_e32 v27, v22
	v_fma_f32 v28, -v8, v24, 1.0
	v_div_scale_f32 v9, vcc, v17, v1, v17
	v_fma_f32 v29, -v10, v25, 1.0
	v_fmac_f32_e32 v24, v28, v24
	v_div_scale_f32 v11, s[4:5], v16, v0, v16
	v_fma_f32 v30, -v20, v26, 1.0
	v_fmac_f32_e32 v25, v29, v25
; __device__ __forceinline__ unsigned cvtpk(float lo, float hi) { f32x2 v = {lo, hi}; bf16x2_t b = __builtin_convertvector(v, bf16x2_t); return __builtin_bit_cast(unsigned, b); }
; __device__ __forceinline__ float bf2f(unsigned u16) { return __uint_as_float(u16 << 16); }
; __device__ __forceinline__ float silu(float g) { return g / (1.f + __expf(-g)); }
; template <int MODE>
; __device__ __forceinline__ void attn_unit(const UnitP& P, ALAS char* lds, const float* __restrict__ sub_gain, const int wv0, unsigned& hgen, unsigned* qctr, const int xcd) {
;     ...
; #pragma unroll
;             for (int d0 = 0; d0 < 4; ++d0)
; #pragma unroll
;                 for (int g = 0; g < 4; ++g) {
;                     const u32x2 gg = *(const u32x2*)(gp + 32 * d0 + 8 * g);
;                     const float y0 = o[d0][4 * g + 0] * inv * silu(bf2f(gg.x & 0xffffu)), y1 = o[d0][4 * g + 1] * inv * silu(bf2f(gg.x >> 16));
;                     const float y2 = o[d0][4 * g + 2] * inv * silu(bf2f(gg.y & 0xffffu)), y3 = o[d0][4 * g + 3] * inv * silu(bf2f(gg.y >> 16));
;                     u32x2 w; w.x = cvtpk(y0, y1); w.y = cvtpk(y2, y3);
;                     *(u32x2*)(mp + 32 * d0 + 8 * g) = w;
	v_mul_f32_e32 v28, v9, v24
	v_div_scale_f32 v21, s[6:7], v19, v3, v19
	v_fma_f32 v31, -v22, v27, 1.0
	v_fmac_f32_e32 v26, v30, v26
	v_mul_f32_e32 v29, v11, v25
	v_fma_f32 v32, -v8, v28, v9
	v_div_scale_f32 v23, s[8:9], v18, v2, v18
	v_fmac_f32_e32 v27, v31, v27
	v_mul_f32_e32 v30, v21, v26
	v_fma_f32 v33, -v10, v29, v11
	v_fmac_f32_e32 v28, v32, v24
	v_mul_f32_e32 v31, v23, v27
	v_fma_f32 v34, -v20, v30, v21
	v_fmac_f32_e32 v29, v33, v25
	v_fma_f32 v8, -v8, v28, v9
	v_fma_f32 v35, -v22, v31, v23
	v_fmac_f32_e32 v30, v34, v26
	v_fma_f32 v9, -v10, v29, v11
	v_div_fmas_f32 v8, v8, v24, v28
	s_mov_b64 vcc, s[4:5]
	v_fmac_f32_e32 v31, v35, v27
	v_fma_f32 v10, -v20, v30, v21
	v_div_fixup_f32 v1, v8, v1, v17
	v_div_fmas_f32 v8, v9, v25, v29
	s_mov_b64 vcc, s[6:7]
	v_fma_f32 v11, -v22, v31, v23
	v_div_fixup_f32 v0, v8, v0, v16
	v_div_fmas_f32 v8, v10, v26, v30
	s_mov_b64 vcc, s[8:9]
	v_pk_mul_f32 v[0:1], v[4:5], v[0:1]
	v_div_fmas_f32 v4, v11, v27, v31
	v_div_fixup_f32 v3, v8, v3, v19
	v_div_fixup_f32 v2, v4, v2, v18
	v_pk_mul_f32 v[2:3], v[6:7], v[2:3]
	v_cvt_pk_bf16_f32 v0, v0, v1
	v_cvt_pk_bf16_f32 v1, v2, v3
	v_mov_b32_e32 v128, v0
	v_mov_b32_e32 v129, v1
	v_mov_b32_e32 v0, v126
	v_mov_b32_e32 v1, v127
	v_pk_mul_f32 v[4:5], v[12:13], v[66:67] op_sel_hi:[1,0]
	v_pk_mul_f32 v[6:7], v[14:15], v[66:67] op_sel_hi:[1,0]
	v_lshlrev_b32_e32 v8, 16, v0
	v_and_b32_e32 v9, 0xffff0000, v0
	v_lshlrev_b32_e32 v10, 16, v1
	v_and_b32_e32 v11, 0xffff0000, v1
	v_mul_f32_e32 v0, 0xbfb8aa3b, v8
	v_mul_f32_e32 v1, 0xbfb8aa3b, v9
	v_exp_f32_e32 v0, v0
	v_exp_f32_e32 v1, v1
	v_mul_f32_e32 v2, 0xbfb8aa3b, v10
	v_mul_f32_e32 v3, 0xbfb8aa3b, v11
	v_exp_f32_e32 v2, v2
	v_exp_f32_e32 v3, v3
	v_pk_add_f32 v[0:1], v[0:1], 1.0 op_sel_hi:[1,0]
	v_pk_add_f32 v[2:3], v[2:3], 1.0 op_sel_hi:[1,0]
	v_div_scale_f32 v12, s[4:5], v1, v1, v9
	v_div_scale_f32 v14, s[4:5], v0, v0, v8
	v_rcp_f32_e32 v20, v12
	v_div_scale_f32 v16, s[6:7], v3, v3, v11
	v_rcp_f32_e32 v21, v14
	v_div_scale_f32 v18, s[8:9], v2, v2, v10
	v_rcp_f32_e32 v22, v16
	v_rcp_f32_e32 v23, v18
	v_fma_f32 v24, -v12, v20, 1.0
	v_div_scale_f32 v13, vcc, v9, v1, v9
	v_fma_f32 v25, -v14, v21, 1.0
	v_fmac_f32_e32 v20, v24, v20
	v_div_scale_f32 v15, s[4:5], v8, v0, v8
	v_fma_f32 v26, -v16, v22, 1.0
	v_fmac_f32_e32 v21, v25, v21
	v_mul_f32_e32 v24, v13, v20
	v_div_scale_f32 v17, s[6:7], v11, v3, v11
	v_fma_f32 v27, -v18, v23, 1.0
	v_fmac_f32_e32 v22, v26, v22
	v_mul_f32_e32 v25, v15, v21
	v_fma_f32 v28, -v12, v24, v13
	v_div_scale_f32 v19, s[8:9], v10, v2, v10
	v_fmac_f32_e32 v23, v27, v23
	v_mul_f32_e32 v26, v17, v22
	v_fma_f32 v29, -v14, v25, v15
	v_fmac_f32_e32 v24, v28, v20
	v_mul_f32_e32 v27, v19, v23
	v_fma_f32 v30, -v16, v26, v17
	v_fmac_f32_e32 v25, v29, v21
	v_fma_f32 v12, -v12, v24, v13
	v_fma_f32 v31, -v18, v27, v19
	v_fmac_f32_e32 v26, v30, v22
	v_fma_f32 v13, -v14, v25, v15
	v_div_fmas_f32 v12, v12, v20, v24
	s_mov_b64 vcc, s[4:5]
	v_fmac_f32_e32 v27, v31, v23
	v_fma_f32 v14, -v16, v26, v17
	v_div_fixup_f32 v1, v12, v1, v9
	v_div_fmas_f32 v9, v13, v21, v25
	s_mov_b64 vcc, s[6:7]
	v_fma_f32 v15, -v18, v27, v19
	v_div_fixup_f32 v0, v9, v0, v8
	v_div_fmas_f32 v8, v14, v22, v26
	s_mov_b64 vcc, s[8:9]
	v_pk_mul_f32 v[0:1], v[4:5], v[0:1]
	v_div_fmas_f32 v4, v15, v23, v27
	v_div_fixup_f32 v3, v8, v3, v11
	v_div_fixup_f32 v2, v4, v2, v10
	v_pk_mul_f32 v[2:3], v[6:7], v[2:3]
	v_cvt_pk_bf16_f32 v0, v0, v1
	v_cvt_pk_bf16_f32 v1, v2, v3
	v_mov_b32_e32 v130, v0
	v_mov_b32_e32 v131, v1
	s_nop 1
	v_permlane32_swap_b32_e32 v128, v130
	v_permlane32_swap_b32_e32 v129, v131
	global_store_dwordx4 v[132:133], v[128:131], off offset:224
	s_branch .LBB0_218
